# attention units: dead m0 save/restore pairs around every LDS-DMA issue removed (4 SALU per key tile per wave)
# baseline (speedup 1.0000x reference)
.LBB0_597:
	s_or_b64 exec, exec, s[2:3]
	s_ashr_i32 s1, s0, 31
	s_lshl_b64 s[2:3], s[0:1], 13
	s_lshl_b32 s1, s6, 8
	s_or_b32 s2, s2, s1
	s_sub_i32 s8, s7, s19
	s_mul_hi_u32 s7, s2, 0xe00
	s_mul_i32 s9, s3, 0xe00
	s_mul_i32 s6, s2, 0xe00
	s_add_i32 s7, s7, s9
	v_readlane_b32 s10, v254, 35
	v_readlane_b32 s11, v254, 36
	s_add_u32 s9, s10, s6
	s_addc_u32 s10, s11, s7
	s_lshl_b32 s6, s5, 6
	s_ashr_i32 s7, s6, 31
	s_lshl_b64 s[36:37], s[6:7], 1
	s_add_u32 s11, s9, s36
	s_addc_u32 s18, s10, s37
	s_add_u32 s6, s12, s36
	s_addc_u32 s7, s13, s37
	s_add_u32 s22, s14, s36
	s_addc_u32 s23, s15, s37
	s_lshl_b32 s9, s0, 8
	s_lshl_b32 s0, s0, 13
	s_lshl_b32 s5, s19, 6
	s_add_i32 s26, s9, 0x4000
	s_or_b32 s10, s5, s0
	v_mov_b32_e32 v14, v191
	s_cmp_eq_u32 s8, 1
	s_waitcnt lgkmcnt(0)
	s_barrier
	s_cselect_b32 s20, 12, 16
	v_readfirstlane_b32 s5, v14
	s_ashr_i32 s17, s5, 6
	v_and_b32_e32 v178, 63, v14
	s_lshl_b32 s44, s17, 5
	s_ashr_i32 s45, s44, 31
	s_mul_i32 s8, s17, 0x1c000
	v_mul_u32_u24_e32 v0, 0x700, v178
	s_mul_hi_i32 s21, s44, 0xe00
	s_add_u32 s24, s11, s8
	v_lshlrev_b32_e32 v0, 1, v0
	s_addc_u32 s25, s18, s21
	v_lshl_add_u64 v[2:3], s[6:7], 0, v[0:1]
	s_lshl_b32 s6, s17, 3
	s_ashr_i32 s7, s6, 31
	v_lshl_add_u64 v[174:175], s[6:7], 1, v[2:3]
	s_lshl_b32 s6, s17, 4
	v_bfe_u32 v0, v14, 2, 4
	v_and_or_b32 v0, s6, 48, v0
	s_ashr_i32 s6, s5, 3
	v_mul_u32_u24_e32 v0, 0x700, v0
	s_andn2_b32 s6, s6, 31
	s_and_b32 s11, s5, 0x3fffffc0
	v_lshlrev_b32_e32 v0, 1, v0
	s_ashr_i32 s7, s6, 31
	v_lshlrev_b32_e32 v179, 3, v14
	s_lshl_b32 s21, s17, 10
	v_lshl_add_u64 v[2:3], s[22:23], 0, v[0:1]
	v_and_b32_e32 v189, 24, v179
	s_cmp_lg_u32 0, -1
	v_lshl_add_u64 v[2:3], s[6:7], 1, v[2:3]
	v_lshlrev_b32_e32 v0, 1, v189
	s_cselect_b32 s6, 0, 0
	v_lshl_add_u64 v[176:177], v[2:3], 0, v[0:1]
	s_add_i32 s21, s21, s6
	v_mad_i64_i32 v[2:3], s[6:7], s26, v217, v[174:175]
	v_and_b32_e32 v180, 31, v14
	v_bfe_u32 v181, v14, 5, 1
	s_mov_b32 m0, s21
	s_nop 0
	global_load_lds_dwordx4 v[2:3], off
	s_add_i32 s22, s21, 0x6000
	v_mad_i64_i32 v[2:3], s[6:7], s26, v217, v[176:177]
	s_mov_b32 m0, s22
	s_nop 0
	global_load_lds_dwordx4 v[2:3], off
	s_add_i32 s7, s9, 0x4040
	v_mul_u32_u24_e32 v0, 0x700, v180
	v_lshlrev_b32_e32 v193, 4, v181
	v_mad_i64_i32 v[2:3], s[26:27], s7, v217, v[174:175]
	s_add_i32 s6, s21, 0x2000
	s_mov_b32 m0, s6
	s_nop 0
	global_load_lds_dwordx4 v[2:3], off
	v_lshl_or_b32 v0, v0, 1, v193
	global_load_dwordx4 v[126:129], v0, s[24:25] offset:1280
	global_load_dwordx4 v[118:121], v0, s[24:25] offset:1312
	global_load_dwordx4 v[106:109], v0, s[24:25] offset:1344
	global_load_dwordx4 v[98:101], v0, s[24:25] offset:1376
	v_lshlrev_b32_e32 v0, 10, v181
	v_lshlrev_b32_e32 v2, 4, v180
	s_add_i32 s8, s9, 0x4080
	v_add3_u32 v197, 0, v0, v2
	v_mad_i64_i32 v[2:3], s[24:25], s8, v217, v[174:175]
	s_add_i32 s6, s21, 0x4000
	s_mov_b32 m0, s6
	s_nop 0
	global_load_lds_dwordx4 v[2:3], off
	s_waitcnt vmcnt(3) lgkmcnt(0)
	s_barrier
	ds_read_b128 v[2:5], v197
	ds_read_b128 v[6:9], v197 offset:512
	s_addk_i32 s9, 0x40c0
	s_lshl_b32 s11, s11, 2
	s_add_i32 s18, s11, 0
	v_lshlrev_b32_e32 v0, 1, v14
	s_mov_b32 s56, 0
	v_and_b32_e32 v192, 32, v0
	s_mov_b32 s57, s56
	v_add_u32_e32 v54, 0, v192
	s_ashr_i32 s5, s5, 7
	s_mov_b32 s58, s56
	s_mov_b32 s59, s56
	s_mov_b32 s60, s56
	s_mov_b32 s61, s56
	s_mov_b32 s62, s56
	s_waitcnt vmcnt(3) lgkmcnt(1)
	v_mfma_f32_32x32x16_bf16 v[34:49], v[2:5], v[126:129], 0
	s_mov_b32 s63, s56
	s_mov_b32 s64, s56
	s_mov_b32 s65, s56
	s_mov_b32 s66, s56
	s_mov_b32 s67, s56
	s_mov_b32 s68, s56
	s_mov_b32 s69, s56
	s_waitcnt lgkmcnt(0)
	v_mfma_f32_32x32x16_bf16 v[18:33], v[6:9], v[126:129], 0
	ds_read_b128 v[2:5], v197 offset:2048
	ds_read_b128 v[6:9], v197 offset:2560
	s_mov_b32 s70, s56
	s_mov_b32 s71, s56
	s_or_b32 s0, s0, s1
	s_mov_b32 s23, 1
	s_movk_i32 s6, 0x4000
	s_mov_b32 s38, -1
	s_waitcnt vmcnt(2) lgkmcnt(1)
	v_mfma_f32_32x32x16_bf16 v[34:49], v[2:5], v[118:121], v[34:49]
	ds_read_b128 v[2:5], v197 offset:4608
	ds_read_b128 v[10:13], v197 offset:4096
	s_movk_i32 s35, 0x2000
	v_and_or_b32 v198, s44, 32, v180
	v_cmp_gt_u32_e64 s[40:41], 32, v178
	v_lshl_add_u32 v194, v180, 2, s18
	v_mov_b32_e32 v200, 0
	s_mov_b32 s33, 64
	s_waitcnt lgkmcnt(2)
	v_mfma_f32_32x32x16_bf16 v[18:33], v[6:9], v[118:121], v[18:33]
	ds_read_b128 v[50:53], v197 offset:6656
	ds_read_b128 v[6:9], v197 offset:6144
	s_waitcnt vmcnt(1) lgkmcnt(2)
	v_mfma_f32_32x32x16_bf16 v[34:49], v[10:13], v[106:109], v[34:49]
	v_mfma_f32_32x32x16_bf16 v[18:33], v[2:5], v[106:109], v[18:33]
	v_lshlrev_b32_e32 v2, 4, v14
	v_and_b32_e32 v0, 0xc0, v2
	v_lshl_or_b32 v0, v181, 8, v0
	v_add3_u32 v195, v54, v189, v0
	s_waitcnt vmcnt(0) lgkmcnt(0)
	v_mfma_f32_32x32x16_bf16 v[34:49], v[6:9], v[98:101], v[34:49]
	v_mov_b64_e32 v[2:3], s[56:57]
	v_mov_b64_e32 v[16:17], s[70:71]
	v_mov_b64_e32 v[4:5], s[58:59]
	v_mov_b64_e32 v[6:7], s[60:61]
	v_mov_b64_e32 v[8:9], s[62:63]
	v_mov_b64_e32 v[10:11], s[64:65]
	v_mov_b64_e32 v[12:13], s[66:67]
	v_mfma_f32_32x32x16_bf16 v[18:33], v[50:53], v[98:101], v[18:33]
	s_nop 15
	s_nop 7
	s_waitcnt vmcnt(0) lgkmcnt(0)
	s_barrier
	v_mov_b64_e32 v[14:15], s[68:69]
	v_max3_f32 v50, v34, v35, v18
	v_max3_f32 v51, v36, v37, v19
	s_nop 0
	v_max3_f32 v50, v50, v20, v21
	v_max3_f32 v51, v51, v40, v41
	s_nop 0
	v_max3_f32 v50, v50, v38, v39
	v_max3_f32 v51, v51, v24, v25
	s_nop 0
	v_max3_f32 v50, v50, v22, v23
	v_max3_f32 v51, v51, v44, v45
	s_nop 0
	v_max3_f32 v50, v50, v42, v43
	v_max3_f32 v51, v51, v28, v29
	s_nop 0
	v_max3_f32 v50, v50, v26, v27
	v_max3_f32 v51, v51, v48, v49
	s_nop 0
	v_max3_f32 v50, v50, v46, v47
	v_max3_f32 v51, v51, v32, v33
	s_nop 0
	v_max3_f32 v50, v50, v30, v31
	s_nop 0
	v_max_f32_e32 v50, v50, v51
	s_nop 0
	v_mov_b32_e32 v51, v50
	s_nop 1
	v_permlane32_swap_b32_e32 v50, v51
	v_max_f32_e32 v50, v50, v51
	s_nop 0
	v_sub_f32_e32 v66, v18, v50
	v_sub_f32_e32 v67, v19, v50
	v_mad_i64_i32 v[18:19], s[24:25], s9, v217, v[174:175]
	s_mov_b32 m0, s21
	s_nop 0
	global_load_lds_dwordx4 v[18:19], off
	v_mad_i64_i32 v[18:19], s[24:25], s7, v217, v[176:177]
	s_add_i32 s9, s21, 0x8000
	s_mov_b32 m0, s9
	s_nop 0
	global_load_lds_dwordx4 v[18:19], off
	ds_read_b128 v[158:161], v197 offset:8192
	ds_read_b128 v[154:157], v197 offset:8704
	ds_read_b128 v[150:153], v197 offset:10240
	ds_read_b128 v[146:149], v197 offset:10752
	ds_read_b128 v[142:145], v197 offset:12288
	ds_read_b128 v[138:141], v197 offset:12800
	ds_read_b128 v[134:137], v197 offset:14336
	ds_read_b128 v[130:133], v197 offset:14848
	v_sub_f32_e32 v34, v34, v50
	v_sub_f32_e32 v35, v35, v50
	v_sub_f32_e32 v36, v36, v50
	v_sub_f32_e32 v37, v37, v50
	v_sub_f32_e32 v38, v38, v50
	v_sub_f32_e32 v39, v39, v50
	v_sub_f32_e32 v40, v40, v50
	v_sub_f32_e32 v41, v41, v50
	v_sub_f32_e32 v42, v42, v50
	v_sub_f32_e32 v43, v43, v50
	v_sub_f32_e32 v44, v44, v50
	v_sub_f32_e32 v45, v45, v50
	v_sub_f32_e32 v46, v46, v50
	v_sub_f32_e32 v47, v47, v50
	v_sub_f32_e32 v48, v48, v50
	v_sub_f32_e32 v49, v49, v50
	v_add_f32_e32 v196, v1, v50
	v_sub_f32_e32 v20, v20, v50
	v_sub_f32_e32 v21, v21, v50
	v_sub_f32_e32 v22, v22, v50
	v_sub_f32_e32 v23, v23, v50
	v_sub_f32_e32 v24, v24, v50
	v_sub_f32_e32 v25, v25, v50
	v_sub_f32_e32 v26, v26, v50
	v_sub_f32_e32 v27, v27, v50
	v_sub_f32_e32 v28, v28, v50
	v_sub_f32_e32 v29, v29, v50
	v_sub_f32_e32 v30, v30, v50
	v_sub_f32_e32 v31, v31, v50
	v_sub_f32_e32 v32, v32, v50
	v_sub_f32_e32 v33, v33, v50
	s_nop 0
	v_exp_f32_e32 v65, v49
	v_exp_f32_e32 v50, v34
	v_exp_f32_e32 v51, v35
	v_exp_f32_e32 v52, v36
	v_exp_f32_e32 v53, v37
	v_exp_f32_e32 v54, v38
	v_exp_f32_e32 v55, v39
	v_exp_f32_e32 v56, v40
	v_exp_f32_e32 v57, v41
	v_exp_f32_e32 v58, v42
	v_exp_f32_e32 v59, v43
	v_exp_f32_e32 v60, v44
	v_exp_f32_e32 v61, v45
	v_exp_f32_e32 v62, v46
	v_exp_f32_e32 v63, v47
	v_exp_f32_e32 v64, v48
	v_exp_f32_e32 v49, v33
	v_exp_f32_e32 v34, v66
	v_exp_f32_e32 v35, v67
	v_exp_f32_e32 v36, v20
	v_exp_f32_e32 v37, v21
	v_exp_f32_e32 v38, v22
	v_exp_f32_e32 v39, v23
	v_exp_f32_e32 v40, v24
	v_exp_f32_e32 v41, v25
	v_exp_f32_e32 v42, v26
	v_exp_f32_e32 v43, v27
	v_exp_f32_e32 v44, v28
	v_exp_f32_e32 v45, v29
	v_exp_f32_e32 v46, v30
	v_exp_f32_e32 v47, v31
	v_exp_f32_e32 v48, v32
	s_add_i32 s24, s5, s4
	s_min_u32 s4, s4, 4
	s_waitcnt vmcnt(2) lgkmcnt(0)
	s_barrier
	v_med3_i32 v199, s24, 4, v218
	s_add_i32 s5, s5, s4
	s_lshl_b32 s1, s4, 6
	v_readfirstlane_b32 s9, v199
	s_mul_i32 s5, s5, 31
	s_sub_i32 s31, s0, s1
	s_bitset1_b32 s0, 7
	v_mov_b64_e32 v[32:33], v[16:17]
	s_add_i32 s25, s20, -5
	s_sub_i32 s26, s19, s9
	s_add_i32 s9, s10, 0xffffff40
	s_addk_i32 s10, 0xff80
	s_sub_i32 s11, 0xe5, s5
	s_sub_i32 s28, s0, s1
	s_sub_i32 s27, 0xc9, s5
	v_mov_b64_e32 v[30:31], v[14:15]
	v_mov_b64_e32 v[28:29], v[12:13]
	v_mov_b64_e32 v[26:27], v[10:11]
	v_mov_b64_e32 v[24:25], v[8:9]
	v_mov_b64_e32 v[22:23], v[6:7]
	v_mov_b64_e32 v[20:21], v[4:5]
	v_mov_b64_e32 v[18:19], v[2:3]

.LBB0_606:
	v_add_u32_e32 v166, s56, v195
	ds_read_b64_tr_b16 v[162:163], v166 offset:24576
	ds_read_b64_tr_b16 v[164:165], v166 offset:25088
	s_waitcnt lgkmcnt(9)
	v_mfma_f32_32x32x16_bf16 v[82:97], v[158:161], v[126:129], v[82:97]
	v_add_f32_e32 v102, v50, v51
	v_add_f32_e32 v102, v52, v102
	v_add_f32_e32 v102, v53, v102
	v_add_f32_e32 v102, v54, v102
	v_add_f32_e32 v102, v55, v102
	v_cvt_pk_bf16_f32 v122, v50, v51
	v_cvt_pk_bf16_f32 v123, v52, v53
	ds_read_b64_tr_b16 v[50:51], v166 offset:28672
	ds_read_b64_tr_b16 v[52:53], v166 offset:29184
	s_waitcnt lgkmcnt(10)
	v_mfma_f32_32x32x16_bf16 v[66:81], v[154:157], v[126:129], v[66:81]
	v_add_f32_e32 v102, v56, v102
	v_add_f32_e32 v102, v57, v102
	v_add_f32_e32 v102, v58, v102
	v_add_f32_e32 v102, v59, v102
	v_cvt_pk_bf16_f32 v124, v54, v55
	v_cvt_pk_bf16_f32 v125, v56, v57
	ds_read_b64_tr_b16 v[54:55], v166 offset:25600
	ds_read_b64_tr_b16 v[56:57], v166 offset:26112
	s_waitcnt lgkmcnt(11)
	v_mfma_f32_32x32x16_bf16 v[82:97], v[150:153], v[118:121], v[82:97]
	v_add_f32_e32 v102, v60, v102
	v_add_f32_e32 v102, v61, v102
	v_add_f32_e32 v102, v62, v102
	v_add_f32_e32 v102, v63, v102
	v_cvt_pk_bf16_f32 v114, v58, v59
	v_cvt_pk_bf16_f32 v115, v60, v61
	ds_read_b64_tr_b16 v[58:59], v166 offset:29696
	ds_read_b64_tr_b16 v[60:61], v166 offset:30208
	s_waitcnt lgkmcnt(12)
	v_mfma_f32_32x32x16_bf16 v[66:81], v[146:149], v[118:121], v[66:81]
	v_add_f32_e32 v102, v64, v102
	v_add_f32_e32 v102, v65, v102
	v_add_f32_e32 v102, v34, v102
	v_add_f32_e32 v102, v35, v102
	v_cvt_pk_bf16_f32 v116, v62, v63
	v_cvt_pk_bf16_f32 v117, v64, v65
	ds_read_b64_tr_b16 v[62:63], v166 offset:26624
	ds_read_b64_tr_b16 v[64:65], v166 offset:27136
	s_waitcnt lgkmcnt(13)
	v_mfma_f32_32x32x16_bf16 v[82:97], v[142:145], v[106:109], v[82:97]
	v_add_f32_e32 v102, v36, v102
	v_add_f32_e32 v102, v37, v102
	v_add_f32_e32 v102, v38, v102
	v_add_f32_e32 v102, v39, v102
	v_cvt_pk_bf16_f32 v110, v34, v35
	v_cvt_pk_bf16_f32 v111, v36, v37
	ds_read_b64_tr_b16 v[34:35], v166 offset:30720
	ds_read_b64_tr_b16 v[36:37], v166 offset:31232
	s_waitcnt lgkmcnt(14)
	v_mfma_f32_32x32x16_bf16 v[66:81], v[138:141], v[106:109], v[66:81]
	v_add_f32_e32 v102, v40, v102
	v_add_f32_e32 v102, v41, v102
	v_add_f32_e32 v102, v42, v102
	v_add_f32_e32 v102, v43, v102
	v_cvt_pk_bf16_f32 v112, v38, v39
	v_cvt_pk_bf16_f32 v113, v40, v41
	ds_read_b64_tr_b16 v[38:39], v166 offset:27648
	ds_read_b64_tr_b16 v[40:41], v166 offset:28160
	s_waitcnt lgkmcnt(14)
	v_mfma_f32_32x32x16_bf16 v[82:97], v[134:137], v[98:101], v[82:97]
	v_add_f32_e32 v102, v44, v102
	v_add_f32_e32 v102, v45, v102
	v_add_f32_e32 v102, v46, v102
	v_add_f32_e32 v134, v47, v102
	v_cvt_pk_bf16_f32 v102, v42, v43
	v_cvt_pk_bf16_f32 v103, v44, v45
	ds_read_b64_tr_b16 v[42:43], v166 offset:31744
	ds_read_b64_tr_b16 v[44:45], v166 offset:32256
	v_mfma_f32_32x32x16_bf16 v[66:81], v[130:133], v[98:101], v[66:81]
	v_add_f32_e32 v104, v48, v134
	v_add_f32_e32 v104, v49, v104
	v_add_f32_e32 v130, 0, v104
	v_cvt_pk_bf16_f32 v104, v46, v47
	v_cvt_pk_bf16_f32 v105, v48, v49
	s_add_i32 s30, s31, s33
	s_sub_i32 s0, s30, 64
	v_mad_i64_i32 v[46:47], s[0:1], s0, v217, v[174:175]
	s_add_i32 s0, s35, s21
	s_cmp_lt_u32 s34, 3
	s_mov_b32 m0, s0
	s_nop 0
	global_load_lds_dwordx4 v[46:47], off
	s_cselect_b32 s0, s7, s9
	s_add_i32 s0, s0, s33
	v_mad_i64_i32 v[46:47], s[0:1], s0, v217, v[176:177]
	s_add_i32 s0, s6, s22
	s_mov_b32 m0, s0
	s_nop 0
	global_load_lds_dwordx4 v[46:47], off
	v_max_f32_e32 v46, v83, v83
	v_max_f32_e32 v47, v82, v82
	v_max_f32_e32 v46, v47, v46
	v_max3_f32 v47, v84, v85, v67
	v_max3_f32 v46, v46, v66, v68
	v_max3_f32 v46, v46, v69, v86
	v_max3_f32 v47, v47, v88, v89
	v_max3_f32 v46, v46, v87, v70
	v_max3_f32 v47, v47, v72, v73
	v_max3_f32 v46, v46, v71, v90
	v_max3_f32 v47, v47, v92, v93
	v_max3_f32 v46, v46, v91, v74
	v_max3_f32 v47, v47, v76, v77
	v_max3_f32 v46, v46, v75, v94
	v_max3_f32 v47, v47, v96, v97
	v_max3_f32 v46, v46, v95, v78
	v_max3_f32 v47, v47, v80, v81
	v_max3_f32 v46, v46, v79, v47
	v_mov_b32_e32 v47, v46
	s_nop 1
	v_permlane32_swap_b32_e32 v46, v47
	v_max_f32_e32 v47, v47, v47
	v_max_f32_e32 v46, v46, v46
	v_max_f32_e32 v46, v46, v47
	v_cmp_lt_f32_e32 vcc, s51, v46
	s_cmp_lg_u64 vcc, 0
	v_add_f32_e32 v166, v200, v130
	s_cselect_b64 s[0:1], -1, 0
	s_cbranch_vccnz .LBB0_622

.LBB0_617:
	s_add_i32 s0, s6, 0x2000
	s_cmpk_lg_i32 s6, 0x4000
	s_cselect_b32 s29, s0, 0
	v_add_u32_e32 v167, s35, v195
	ds_read_b64_tr_b16 v[162:163], v167 offset:24576
	ds_read_b64_tr_b16 v[164:165], v167 offset:25088
	s_waitcnt lgkmcnt(9)
	v_mfma_f32_32x32x16_bf16 v[50:65], v[158:161], v[126:129], v[50:65]
	v_add_f32_e32 v102, v82, v83
	v_add_f32_e32 v102, v84, v102
	v_add_f32_e32 v102, v85, v102
	v_add_f32_e32 v102, v86, v102
	v_add_f32_e32 v102, v87, v102
	v_cvt_pk_bf16_f32 v122, v82, v83
	v_cvt_pk_bf16_f32 v123, v84, v85
	ds_read_b64_tr_b16 v[82:83], v167 offset:28672
	ds_read_b64_tr_b16 v[84:85], v167 offset:29184
	s_waitcnt lgkmcnt(10)
	v_mfma_f32_32x32x16_bf16 v[34:49], v[154:157], v[126:129], v[34:49]
	v_add_f32_e32 v102, v88, v102
	v_add_f32_e32 v102, v89, v102
	v_add_f32_e32 v102, v90, v102
	v_add_f32_e32 v102, v91, v102
	v_cvt_pk_bf16_f32 v124, v86, v87
	v_cvt_pk_bf16_f32 v125, v88, v89
	ds_read_b64_tr_b16 v[86:87], v167 offset:25600
	ds_read_b64_tr_b16 v[88:89], v167 offset:26112
	s_waitcnt lgkmcnt(11)
	v_mfma_f32_32x32x16_bf16 v[50:65], v[150:153], v[118:121], v[50:65]
	v_add_f32_e32 v102, v92, v102
	v_add_f32_e32 v102, v93, v102
	v_add_f32_e32 v102, v94, v102
	v_add_f32_e32 v102, v95, v102
	v_cvt_pk_bf16_f32 v114, v90, v91
	v_cvt_pk_bf16_f32 v115, v92, v93
	ds_read_b64_tr_b16 v[90:91], v167 offset:29696
	ds_read_b64_tr_b16 v[92:93], v167 offset:30208
	s_waitcnt lgkmcnt(12)
	v_mfma_f32_32x32x16_bf16 v[34:49], v[146:149], v[118:121], v[34:49]
	v_add_f32_e32 v102, v96, v102
	v_add_f32_e32 v102, v97, v102
	v_add_f32_e32 v102, v66, v102
	v_add_f32_e32 v102, v67, v102
	v_cvt_pk_bf16_f32 v116, v94, v95
	v_cvt_pk_bf16_f32 v117, v96, v97
	ds_read_b64_tr_b16 v[94:95], v167 offset:26624
	ds_read_b64_tr_b16 v[96:97], v167 offset:27136
	s_waitcnt lgkmcnt(13)
	v_mfma_f32_32x32x16_bf16 v[50:65], v[142:145], v[106:109], v[50:65]
	v_add_f32_e32 v102, v68, v102
	v_add_f32_e32 v102, v69, v102
	v_add_f32_e32 v102, v70, v102
	v_add_f32_e32 v102, v71, v102
	v_cvt_pk_bf16_f32 v110, v66, v67
	v_cvt_pk_bf16_f32 v111, v68, v69
	ds_read_b64_tr_b16 v[66:67], v167 offset:30720
	ds_read_b64_tr_b16 v[68:69], v167 offset:31232
	s_waitcnt lgkmcnt(14)
	v_mfma_f32_32x32x16_bf16 v[34:49], v[138:141], v[106:109], v[34:49]
	v_add_f32_e32 v102, v72, v102
	v_add_f32_e32 v102, v73, v102
	v_add_f32_e32 v102, v74, v102
	v_add_f32_e32 v102, v75, v102
	v_cvt_pk_bf16_f32 v112, v70, v71
	v_cvt_pk_bf16_f32 v113, v72, v73
	ds_read_b64_tr_b16 v[70:71], v167 offset:27648
	ds_read_b64_tr_b16 v[72:73], v167 offset:28160
	s_waitcnt lgkmcnt(14)
	v_mfma_f32_32x32x16_bf16 v[50:65], v[134:137], v[98:101], v[50:65]
	v_add_f32_e32 v102, v76, v102
	v_add_f32_e32 v102, v77, v102
	v_add_f32_e32 v102, v78, v102
	v_add_f32_e32 v134, v79, v102
	v_cvt_pk_bf16_f32 v102, v74, v75
	v_cvt_pk_bf16_f32 v103, v76, v77
	ds_read_b64_tr_b16 v[74:75], v167 offset:31744
	ds_read_b64_tr_b16 v[76:77], v167 offset:32256
	v_mfma_f32_32x32x16_bf16 v[34:49], v[130:133], v[98:101], v[34:49]
	v_add_f32_e32 v104, v80, v134
	v_add_f32_e32 v104, v81, v104
	v_add_f32_e32 v130, 0, v104
	v_cvt_pk_bf16_f32 v104, v78, v79
	v_cvt_pk_bf16_f32 v105, v80, v81
	v_mad_i64_i32 v[78:79], s[0:1], s30, v217, v[174:175]
	s_add_i32 s0, s6, s21
	s_cmp_lt_u32 s34, 2
	s_mov_b32 m0, s0
	s_nop 0
	global_load_lds_dwordx4 v[78:79], off
	s_cselect_b32 s0, s8, s10
	s_add_i32 s0, s0, s33
	v_mad_i64_i32 v[78:79], s[0:1], s0, v217, v[176:177]
	s_add_i32 s0, s29, s22
	s_mov_b32 m0, s0
	s_nop 0
	global_load_lds_dwordx4 v[78:79], off
	v_max_f32_e32 v78, v51, v51
	v_max_f32_e32 v79, v50, v50
	v_max_f32_e32 v78, v79, v78
	v_max3_f32 v79, v52, v53, v35
	v_max3_f32 v78, v78, v34, v36
	v_max3_f32 v78, v78, v37, v54
	v_max3_f32 v79, v79, v56, v57
	v_max3_f32 v78, v78, v55, v38
	v_max3_f32 v79, v79, v40, v41
	v_max3_f32 v78, v78, v39, v58
	v_max3_f32 v79, v79, v60, v61
	v_max3_f32 v78, v78, v59, v42
	v_max3_f32 v79, v79, v44, v45
	v_max3_f32 v78, v78, v43, v62
	v_max3_f32 v79, v79, v64, v65
	v_max3_f32 v78, v78, v63, v46
	v_max3_f32 v79, v79, v48, v49
	v_max3_f32 v78, v78, v47, v79
	v_mov_b32_e32 v79, v78
	s_nop 1
	v_permlane32_swap_b32_e32 v78, v79
	v_max_f32_e32 v79, v79, v79
	v_max_f32_e32 v78, v78, v78
	v_max_f32_e32 v78, v78, v79
	v_cmp_lt_f32_e32 vcc, s51, v78
	s_cmp_lg_u64 vcc, 0
	v_add_f32_e32 v200, v166, v130
	s_cselect_b64 s[0:1], -1, 0
	s_cbranch_vccnz .LBB0_625

.LBB0_635:
	v_add_u32_e32 v166, s6, v195
	ds_read_b64_tr_b16 v[162:163], v166 offset:24576
	ds_read_b64_tr_b16 v[164:165], v166 offset:25088
	s_waitcnt lgkmcnt(9)
	v_mfma_f32_32x32x16_bf16 v[82:97], v[158:161], v[126:129], v[82:97]
	v_add_f32_e32 v102, v50, v51
	v_add_f32_e32 v102, v52, v102
	v_add_f32_e32 v102, v53, v102
	v_add_f32_e32 v102, v54, v102
	v_add_f32_e32 v102, v55, v102
	v_cvt_pk_bf16_f32 v122, v50, v51
	v_cvt_pk_bf16_f32 v123, v52, v53
	ds_read_b64_tr_b16 v[50:51], v166 offset:28672
	ds_read_b64_tr_b16 v[52:53], v166 offset:29184
	s_waitcnt lgkmcnt(10)
	v_mfma_f32_32x32x16_bf16 v[66:81], v[154:157], v[126:129], v[66:81]
	v_add_f32_e32 v102, v56, v102
	v_add_f32_e32 v102, v57, v102
	v_add_f32_e32 v102, v58, v102
	v_add_f32_e32 v102, v59, v102
	v_cvt_pk_bf16_f32 v124, v54, v55
	v_cvt_pk_bf16_f32 v125, v56, v57
	ds_read_b64_tr_b16 v[54:55], v166 offset:25600
	ds_read_b64_tr_b16 v[56:57], v166 offset:26112
	s_waitcnt lgkmcnt(11)
	v_mfma_f32_32x32x16_bf16 v[82:97], v[150:153], v[118:121], v[82:97]
	v_add_f32_e32 v102, v60, v102
	v_add_f32_e32 v102, v61, v102
	v_add_f32_e32 v102, v62, v102
	v_add_f32_e32 v102, v63, v102
	v_cvt_pk_bf16_f32 v114, v58, v59
	v_cvt_pk_bf16_f32 v115, v60, v61
	ds_read_b64_tr_b16 v[58:59], v166 offset:29696
	ds_read_b64_tr_b16 v[60:61], v166 offset:30208
	s_waitcnt lgkmcnt(12)
	v_mfma_f32_32x32x16_bf16 v[66:81], v[146:149], v[118:121], v[66:81]
	v_add_f32_e32 v102, v64, v102
	v_add_f32_e32 v102, v65, v102
	v_add_f32_e32 v102, v34, v102
	v_add_f32_e32 v102, v35, v102
	v_cvt_pk_bf16_f32 v116, v62, v63
	v_cvt_pk_bf16_f32 v117, v64, v65
	ds_read_b64_tr_b16 v[62:63], v166 offset:26624
	ds_read_b64_tr_b16 v[64:65], v166 offset:27136
	s_waitcnt lgkmcnt(13)
	v_mfma_f32_32x32x16_bf16 v[82:97], v[142:145], v[106:109], v[82:97]
	v_add_f32_e32 v102, v36, v102
	v_add_f32_e32 v102, v37, v102
	v_add_f32_e32 v102, v38, v102
	v_add_f32_e32 v102, v39, v102
	v_cvt_pk_bf16_f32 v110, v34, v35
	v_cvt_pk_bf16_f32 v111, v36, v37
	ds_read_b64_tr_b16 v[34:35], v166 offset:30720
	ds_read_b64_tr_b16 v[36:37], v166 offset:31232
	s_waitcnt lgkmcnt(14)
	v_mfma_f32_32x32x16_bf16 v[66:81], v[138:141], v[106:109], v[66:81]
	v_add_f32_e32 v102, v40, v102
	v_add_f32_e32 v102, v41, v102
	v_add_f32_e32 v102, v42, v102
	v_add_f32_e32 v102, v43, v102
	v_cvt_pk_bf16_f32 v112, v38, v39
	v_cvt_pk_bf16_f32 v113, v40, v41
	ds_read_b64_tr_b16 v[38:39], v166 offset:27648
	ds_read_b64_tr_b16 v[40:41], v166 offset:28160
	s_waitcnt lgkmcnt(14)
	v_mfma_f32_32x32x16_bf16 v[82:97], v[134:137], v[98:101], v[82:97]
	v_add_f32_e32 v102, v44, v102
	v_add_f32_e32 v102, v45, v102
	v_add_f32_e32 v102, v46, v102
	v_add_f32_e32 v134, v47, v102
	v_cvt_pk_bf16_f32 v102, v42, v43
	v_cvt_pk_bf16_f32 v103, v44, v45
	ds_read_b64_tr_b16 v[42:43], v166 offset:31744
	ds_read_b64_tr_b16 v[44:45], v166 offset:32256
	v_mfma_f32_32x32x16_bf16 v[66:81], v[130:133], v[98:101], v[66:81]
	v_add_f32_e32 v104, v48, v134
	v_add_f32_e32 v104, v49, v104
	v_add_f32_e32 v130, 0, v104
	v_cvt_pk_bf16_f32 v104, v46, v47
	v_cvt_pk_bf16_f32 v105, v48, v49
	s_cmp_ge_u32 s35, s31
	s_cselect_b64 s[4:5], -1, 0
	s_and_b64 vcc, exec, s[4:5]
	s_cbranch_vccnz .LBB0_637
	v_mad_i64_i32 v[46:47], s[0:1], s28, v217, v[174:175]
	s_add_i32 s0, s29, s21
	s_mov_b32 m0, s0
	s_nop 0
	global_load_lds_dwordx4 v[46:47], off
.LBB0_637:
	s_add_i32 s0, s28, 0xffffff80
	v_mad_i64_i32 v[46:47], s[0:1], s0, v217, v[176:177]
	s_add_i32 s0, s30, s22
	s_mov_b32 m0, s0
	s_nop 0
	global_load_lds_dwordx4 v[46:47], off
	v_max_f32_e32 v46, v83, v83
	v_max_f32_e32 v47, v82, v82
	v_max_f32_e32 v46, v47, v46
	v_max3_f32 v47, v84, v85, v67
	v_max3_f32 v46, v46, v66, v68
	v_max3_f32 v46, v46, v69, v86
	v_max3_f32 v47, v47, v88, v89
	v_max3_f32 v46, v46, v87, v70
	v_max3_f32 v47, v47, v72, v73
	v_max3_f32 v46, v46, v71, v90
	v_max3_f32 v47, v47, v92, v93
	v_max3_f32 v46, v46, v91, v74
	v_max3_f32 v47, v47, v76, v77
	v_max3_f32 v46, v46, v75, v94
	v_max3_f32 v47, v47, v96, v97
	v_max3_f32 v46, v46, v95, v78
	v_max3_f32 v47, v47, v80, v81
	v_max3_f32 v46, v46, v79, v47
	v_mov_b32_e32 v47, v46
	s_nop 1
	v_permlane32_swap_b32_e32 v46, v47
	v_max_f32_e32 v47, v47, v47
	v_max_f32_e32 v46, v46, v46
	v_max_f32_e32 v46, v46, v47
	v_cmp_lt_f32_e32 vcc, s51, v46
	s_cmp_lg_u64 vcc, 0
	v_add_f32_e32 v200, v200, v130
	s_cselect_b64 s[0:1], -1, 0
	s_cbranch_vccnz .LBB0_678

.LBB0_651:
	v_add_u32_e32 v186, s29, v195
	ds_read_b64_tr_b16 v[170:171], v186 offset:24576
	ds_read_b64_tr_b16 v[172:173], v186 offset:25088
	s_waitcnt lgkmcnt(9)
	v_mfma_f32_32x32x16_bf16 v[50:65], v[158:161], v[126:129], v[50:65]
	v_add_f32_e32 v102, v82, v83
	v_add_f32_e32 v102, v84, v102
	v_add_f32_e32 v102, v85, v102
	v_add_f32_e32 v102, v86, v102
	v_add_f32_e32 v102, v87, v102
	v_cvt_pk_bf16_f32 v122, v82, v83
	v_cvt_pk_bf16_f32 v123, v84, v85
	ds_read_b64_tr_b16 v[166:167], v186 offset:28672
	ds_read_b64_tr_b16 v[168:169], v186 offset:29184
	s_waitcnt lgkmcnt(10)
	v_mfma_f32_32x32x16_bf16 v[34:49], v[154:157], v[126:129], v[34:49]
	v_add_f32_e32 v82, v88, v102
	v_add_f32_e32 v82, v89, v82
	v_add_f32_e32 v82, v90, v82
	v_add_f32_e32 v82, v91, v82
	v_cvt_pk_bf16_f32 v124, v86, v87
	v_cvt_pk_bf16_f32 v125, v88, v89
	ds_read_b64_tr_b16 v[162:163], v186 offset:25600
	ds_read_b64_tr_b16 v[164:165], v186 offset:26112
	s_waitcnt lgkmcnt(11)
	v_mfma_f32_32x32x16_bf16 v[50:65], v[150:153], v[118:121], v[50:65]
	v_add_f32_e32 v82, v92, v82
	v_add_f32_e32 v82, v93, v82
	v_add_f32_e32 v82, v94, v82
	v_add_f32_e32 v82, v95, v82
	v_cvt_pk_bf16_f32 v114, v90, v91
	v_cvt_pk_bf16_f32 v115, v92, v93
	ds_read_b64_tr_b16 v[90:91], v186 offset:29696
	ds_read_b64_tr_b16 v[92:93], v186 offset:30208
	s_waitcnt lgkmcnt(12)
	v_mfma_f32_32x32x16_bf16 v[34:49], v[146:149], v[118:121], v[34:49]
	v_add_f32_e32 v82, v96, v82
	v_add_f32_e32 v82, v97, v82
	v_add_f32_e32 v82, v66, v82
	v_add_f32_e32 v82, v67, v82
	v_cvt_pk_bf16_f32 v116, v94, v95
	v_cvt_pk_bf16_f32 v117, v96, v97
	ds_read_b64_tr_b16 v[86:87], v186 offset:26624
	ds_read_b64_tr_b16 v[88:89], v186 offset:27136
	s_waitcnt lgkmcnt(13)
	v_mfma_f32_32x32x16_bf16 v[50:65], v[142:145], v[106:109], v[50:65]
	v_add_f32_e32 v82, v68, v82
	v_add_f32_e32 v82, v69, v82
	v_add_f32_e32 v82, v70, v82
	v_add_f32_e32 v94, v71, v82
	v_cvt_pk_bf16_f32 v110, v66, v67
	v_cvt_pk_bf16_f32 v111, v68, v69
	ds_read_b64_tr_b16 v[82:83], v186 offset:30720
	ds_read_b64_tr_b16 v[84:85], v186 offset:31232
	s_waitcnt lgkmcnt(14)
	v_mfma_f32_32x32x16_bf16 v[34:49], v[138:141], v[106:109], v[34:49]
	v_add_f32_e32 v66, v72, v94
	v_add_f32_e32 v66, v73, v66
	v_add_f32_e32 v66, v74, v66
	v_add_f32_e32 v66, v75, v66
	v_cvt_pk_bf16_f32 v112, v70, v71
	v_cvt_pk_bf16_f32 v113, v72, v73
	ds_read_b64_tr_b16 v[70:71], v186 offset:27648
	ds_read_b64_tr_b16 v[72:73], v186 offset:28160
	s_waitcnt lgkmcnt(14)
	v_mfma_f32_32x32x16_bf16 v[50:65], v[134:137], v[98:101], v[50:65]
	v_add_f32_e32 v66, v76, v66
	v_add_f32_e32 v66, v77, v66
	v_add_f32_e32 v66, v78, v66
	v_add_f32_e32 v94, v79, v66
	v_cvt_pk_bf16_f32 v102, v74, v75
	v_cvt_pk_bf16_f32 v103, v76, v77
	ds_read_b64_tr_b16 v[66:67], v186 offset:31744
	ds_read_b64_tr_b16 v[68:69], v186 offset:32256
	v_mfma_f32_32x32x16_bf16 v[34:49], v[130:133], v[98:101], v[34:49]
	v_add_f32_e32 v74, v80, v94
	v_add_f32_e32 v74, v81, v74
	v_add_f32_e32 v74, 0, v74
	v_cvt_pk_bf16_f32 v104, v78, v79
	v_cvt_pk_bf16_f32 v105, v80, v81
	s_cmp_ge_u32 s35, s34
	s_cselect_b64 s[0:1], -1, 0
	s_and_b64 vcc, exec, s[0:1]
	s_cbranch_vccnz .LBB0_653
	s_add_i32 s6, s28, 64
	v_mad_i64_i32 v[76:77], s[6:7], s6, v217, v[174:175]
	s_add_i32 s6, s30, s21
	s_mov_b32 m0, s6
	s_nop 0
	global_load_lds_dwordx4 v[76:77], off
.LBB0_653:
	s_add_i32 s6, s30, 0x2000
	s_cmpk_lg_i32 s30, 0x4000
	s_cselect_b32 s29, s6, 0
	s_add_i32 s35, s35, 2
	s_cmp_lt_u32 s35, s20
	s_cselect_b64 s[8:9], -1, 0
	s_cmp_ge_u32 s35, s20
	s_cbranch_scc1 .LBB0_655
	s_sub_i32 s6, s28, 64
	v_mad_i64_i32 v[76:77], s[6:7], s6, v217, v[176:177]
	s_add_i32 s6, s29, s22
	s_mov_b32 m0, s6
	s_nop 0
	global_load_lds_dwordx4 v[76:77], off

.LBB0_706:
	s_mul_hi_i32 s0, s14, 0x2aaaaaab
	s_lshr_b32 s1, s0, 31
	s_ashr_i32 s0, s0, 5
	s_add_i32 s0, s0, s1
	s_mul_i32 s1, s0, 0xc0
	s_sub_i32 s1, s14, s1
	s_and_b32 s2, s1, 3
	s_bfe_u32 s4, s1, 0x10002
	s_mul_i32 s2, s2, 24
	s_ashr_i32 s1, s1, 3
	s_add_i32 s5, s2, s1
	s_bfe_i32 s2, s5, 0x80000
	s_bfe_u32 s2, s2, 0x5000a
	s_add_i32 s2, s5, s2
	s_bfe_i32 s2, s2, 0x80000
	s_mul_i32 s1, s4, 3
	s_bfe_u32 s2, s2, 0x80005
	s_add_i32 s6, s1, s2
	s_ashr_i32 s1, s0, 31
	s_lshl_b64 s[2:3], s[0:1], 13
	s_lshl_b32 s1, s5, 8
	s_and_b32 s1, s1, 0x1f00
	s_or_b32 s2, s2, s1
	s_mul_hi_u32 s5, s2, 0xe00
	s_mul_i32 s7, s3, 0xe00
	s_mul_i32 s1, s2, 0xe00
	s_add_i32 s5, s5, s7
	v_readlane_b32 s8, v254, 35
	v_readlane_b32 s9, v254, 36
	s_add_u32 s1, s8, s1
	s_addc_u32 s5, s9, s5
	s_lshl_b32 s16, s6, 6
	s_lshl_b32 s6, s6, 7
	s_add_u32 s1, s1, s6
	s_addc_u32 s5, s5, 0
	s_lshl_b32 s4, s4, 7
	s_add_u32 s6, s10, s4
	s_addc_u32 s7, s11, 0
	v_mov_b32_e32 v42, v191
	s_add_u32 s18, s12, s4
	s_addc_u32 s19, s13, 0
	v_readfirstlane_b32 s17, v42
	s_ashr_i32 s15, s17, 6
	s_lshl_b32 s8, s0, 8
	s_lshl_b32 s36, s15, 5
	s_lshl_b32 s9, s0, 13
	s_add_i32 s20, s8, 0x4000
	v_and_b32_e32 v189, 63, v42
	s_ashr_i32 s37, s36, 31
	s_mul_i32 s0, s15, 0x1c000
	s_mul_hi_i32 s4, s36, 0xe00
	s_add_u32 s22, s1, s0
	v_mul_u32_u24_e32 v0, 0x700, v189
	s_addc_u32 s23, s5, s4
	v_lshlrev_b32_e32 v0, 1, v0
	s_lshl_b32 s0, s15, 3
	v_lshl_add_u64 v[2:3], s[6:7], 0, v[0:1]
	s_ashr_i32 s1, s0, 31
	v_lshl_add_u64 v[192:193], s[0:1], 1, v[2:3]
	s_lshl_b32 s0, s15, 4
	v_bfe_u32 v0, v42, 2, 4
	v_and_or_b32 v0, s0, 48, v0
	v_mul_u32_u24_e32 v0, 0x700, v0
	s_ashr_i32 s0, s17, 3
	v_lshlrev_b32_e32 v0, 1, v0
	s_andn2_b32 s0, s0, 31
	v_lshl_add_u64 v[2:3], s[18:19], 0, v[0:1]
	s_ashr_i32 s1, s0, 31
	v_lshlrev_b32_e32 v198, 3, v42
	s_and_b32 s4, s17, 0x3fffffc0
	v_lshl_add_u64 v[2:3], s[0:1], 1, v[2:3]
	v_and_b32_e32 v201, 24, v198
	s_lshl_b32 s0, s15, 10
	v_lshlrev_b32_e32 v0, 1, v201
	s_cmp_lg_u32 0, -1
	v_lshl_add_u64 v[194:195], v[2:3], 0, v[0:1]
	s_cselect_b32 s1, 0, 0
	v_and_b32_e32 v199, 31, v42
	v_bfe_u32 v200, v42, 5, 1
	s_add_i32 s18, s0, s1
	v_mad_i64_i32 v[2:3], s[0:1], s9, v217, v[192:193]
	s_mov_b32 m0, s18
	s_nop 0
	global_load_lds_dwordx4 v[2:3], off
	s_add_i32 s19, s18, 0x6000
	v_mad_i64_i32 v[82:83], s[0:1], s9, v217, v[194:195]
	s_mov_b32 m0, s19
	s_nop 0
	global_load_lds_dwordx4 v[82:83], off
	s_or_b32 s1, s9, 64
	v_mul_u32_u24_e32 v0, 0x700, v199
	v_lshlrev_b32_e32 v203, 4, v200
	v_mad_i64_i32 v[2:3], s[6:7], s1, v217, v[192:193]
	s_add_i32 s0, s18, 0x2000
	s_mov_b32 m0, s0
	s_nop 0
	global_load_lds_dwordx4 v[2:3], off
	v_lshl_or_b32 v0, v0, 1, v203
	global_load_dwordx4 v[142:145], v0, s[22:23]
	global_load_dwordx4 v[138:141], v0, s[22:23] offset:32
	global_load_dwordx4 v[130:133], v0, s[22:23] offset:64
	global_load_dwordx4 v[122:125], v0, s[22:23] offset:96
	v_lshlrev_b32_e32 v2, 10, v200
	v_lshlrev_b32_e32 v3, 4, v199
	v_add3_u32 v206, 0, v2, v3
	v_mov_b32_e32 v2, v1
	v_mov_b32_e32 v3, v1
	v_mov_b32_e32 v4, v1
	v_mov_b32_e32 v5, v1
	v_mov_b32_e32 v6, v1
	v_mov_b32_e32 v7, v1
	v_mov_b32_e32 v8, v1
	v_mov_b32_e32 v9, v1
	v_mov_b32_e32 v10, v1
	v_mov_b32_e32 v11, v1
	v_mov_b32_e32 v12, v1
	v_mov_b32_e32 v13, v1
	v_mov_b32_e32 v14, v1
	v_mov_b32_e32 v15, v1
	v_mov_b32_e32 v0, v1
	v_mov_b64_e32 v[16:17], v[14:15]
	v_mov_b64_e32 v[14:15], v[12:13]
	v_mov_b64_e32 v[12:13], v[10:11]
	v_mov_b64_e32 v[10:11], v[8:9]
	v_mov_b64_e32 v[8:9], v[6:7]
	v_mov_b64_e32 v[6:7], v[4:5]
	v_mov_b64_e32 v[4:5], v[2:3]
	v_mov_b64_e32 v[2:3], v[0:1]
	s_or_b32 s0, s9, 0x80
	v_mad_i64_i32 v[18:19], s[6:7], s0, v217, v[192:193]
	s_add_i32 s0, s18, 0x4000
	s_mov_b32 m0, s0
	s_nop 0
	global_load_lds_dwordx4 v[18:19], off
	s_waitcnt vmcnt(3) lgkmcnt(0)
	s_barrier
	ds_read_b128 v[34:37], v206
	ds_read_b128 v[38:41], v206 offset:512
	s_waitcnt vmcnt(3) lgkmcnt(1)
	v_mfma_f32_32x32x16_bf16 v[18:33], v[34:37], v[142:145], v[2:17]
	v_lshlrev_b32_e32 v0, 1, v42
	v_and_b32_e32 v202, 32, v0
	v_lshlrev_b32_e32 v0, 4, v42
	s_lshl_b32 s4, s4, 2
	s_add_i32 s17, s4, 0
	s_or_b32 s4, s9, 0xc0
	v_and_b32_e32 v0, 0xc0, v0
	s_waitcnt lgkmcnt(0)
	v_mfma_f32_32x32x16_bf16 v[2:17], v[38:41], v[142:145], v[2:17]
	ds_read_b128 v[34:37], v206 offset:2048
	ds_read_b128 v[38:41], v206 offset:2560
	v_lshl_or_b32 v0, v200, 8, v0
	v_add_u32_e32 v84, 0, v202
	v_mov_b32_e32 v224, 0
	s_movk_i32 s21, 0x4000
	s_mov_b32 s23, -1
	s_mov_b32 s0, 0
	s_waitcnt vmcnt(2) lgkmcnt(1)
	v_mfma_f32_32x32x16_bf16 v[18:33], v[34:37], v[138:141], v[18:33]
	s_movk_i32 s24, 0x2000
	v_add3_u32 v207, v84, v201, v0
	v_cmp_gt_u32_e64 s[40:41], 32, v189
	v_lshl_add_u32 v204, v199, 2, s17
	v_lshl_add_u64 v[196:197], v[82:83], 0, s[28:29]
	s_waitcnt lgkmcnt(0)
	v_mfma_f32_32x32x16_bf16 v[2:17], v[38:41], v[138:141], v[2:17]
	ds_read_b128 v[34:37], v206 offset:4096
	ds_read_b128 v[38:41], v206 offset:4608
	s_waitcnt vmcnt(1) lgkmcnt(1)
	v_mfma_f32_32x32x16_bf16 v[18:33], v[34:37], v[130:133], v[18:33]
	s_waitcnt lgkmcnt(0)
	v_mfma_f32_32x32x16_bf16 v[2:17], v[38:41], v[130:133], v[2:17]
	ds_read_b128 v[34:37], v206 offset:6144
	ds_read_b128 v[38:41], v206 offset:6656
	s_waitcnt vmcnt(0) lgkmcnt(1)
	v_mfma_f32_32x32x16_bf16 v[18:33], v[34:37], v[122:125], v[18:33]
	s_waitcnt lgkmcnt(0)
	v_mfma_f32_32x32x16_bf16 v[2:17], v[38:41], v[122:125], v[2:17]
	s_nop 15
	s_nop 7
	s_nop 0
	v_max3_f32 v34, v18, v19, v2
	v_max3_f32 v35, v20, v21, v3
	s_nop 0
	v_max3_f32 v34, v34, v4, v5
	v_max3_f32 v35, v35, v24, v25
	s_nop 0
	v_max3_f32 v34, v34, v22, v23
	v_max3_f32 v35, v35, v8, v9
	s_nop 0
	v_max3_f32 v34, v34, v6, v7
	v_max3_f32 v35, v35, v28, v29
	s_nop 0
	v_max3_f32 v34, v34, v26, v27
	v_max3_f32 v35, v35, v12, v13
	s_nop 0
	v_max3_f32 v34, v34, v10, v11
	v_max3_f32 v35, v35, v32, v33
	s_nop 0
	v_max3_f32 v34, v34, v30, v31
	v_max3_f32 v35, v35, v16, v17
	s_nop 0
	v_max3_f32 v34, v34, v14, v15
	s_nop 0
	v_max_f32_e32 v34, v34, v35
	s_nop 0
	v_mov_b32_e32 v35, v34
	s_nop 1
	v_permlane32_swap_b32_e32 v34, v35
	v_max_f32_e32 v34, v34, v35
	s_nop 0
	v_add_f32_e32 v205, v1, v34
	v_sub_f32_e32 v18, v18, v34
	v_sub_f32_e32 v2, v2, v34
	v_sub_f32_e32 v19, v19, v34
	v_sub_f32_e32 v3, v3, v34
	v_sub_f32_e32 v20, v20, v34
	v_sub_f32_e32 v4, v4, v34
	v_sub_f32_e32 v21, v21, v34
	v_sub_f32_e32 v5, v5, v34
	v_sub_f32_e32 v22, v22, v34
	v_sub_f32_e32 v6, v6, v34
	v_sub_f32_e32 v23, v23, v34
	v_sub_f32_e32 v7, v7, v34
	v_sub_f32_e32 v24, v24, v34
	v_sub_f32_e32 v8, v8, v34
	v_sub_f32_e32 v25, v25, v34
	v_sub_f32_e32 v9, v9, v34
	v_sub_f32_e32 v26, v26, v34
	v_sub_f32_e32 v10, v10, v34
	v_sub_f32_e32 v27, v27, v34
	v_sub_f32_e32 v11, v11, v34
	v_sub_f32_e32 v28, v28, v34
	v_sub_f32_e32 v12, v12, v34
	v_sub_f32_e32 v29, v29, v34
	v_sub_f32_e32 v13, v13, v34
	v_sub_f32_e32 v30, v30, v34
	v_sub_f32_e32 v14, v14, v34
	v_sub_f32_e32 v31, v31, v34
	v_sub_f32_e32 v15, v15, v34
	v_sub_f32_e32 v32, v32, v34
	v_sub_f32_e32 v16, v16, v34
	v_sub_f32_e32 v33, v33, v34
	v_sub_f32_e32 v17, v17, v34
	s_nop 0
	v_xor_b32_e32 v34, 0x80000000, v205
	v_mov_b32_e32 v35, v34
	v_mov_b32_e32 v36, v34
	v_mov_b32_e32 v37, v34
	v_mov_b32_e32 v38, v34
	v_mov_b32_e32 v39, v34
	v_mov_b32_e32 v40, v34
	v_mov_b32_e32 v41, v34
	v_mov_b32_e32 v42, v34
	v_mov_b32_e32 v43, v34
	v_mov_b32_e32 v44, v34
	v_mov_b32_e32 v45, v34
	v_mov_b32_e32 v46, v34
	v_mov_b32_e32 v47, v34
	v_mov_b32_e32 v48, v34
	v_mov_b32_e32 v49, v34
	s_waitcnt vmcnt(0) lgkmcnt(0)
	s_barrier
	v_exp_f32_e32 v50, v2
	v_exp_f32_e32 v51, v3
	v_mad_i64_i32 v[2:3], s[4:5], s4, v217, v[192:193]
	s_mov_b32 m0, s18
	s_nop 0
	global_load_lds_dwordx4 v[2:3], off
	v_exp_f32_e32 v66, v18
	v_mad_i64_i32 v[2:3], s[4:5], s1, v217, v[194:195]
	s_add_i32 s1, s18, 0x8000
	s_mov_b32 m0, s1
	s_nop 0
	global_load_lds_dwordx4 v[2:3], off
	ds_read_b128 v[174:177], v206 offset:8192
	ds_read_b128 v[170:173], v206 offset:8704
	ds_read_b128 v[166:169], v206 offset:10240
	ds_read_b128 v[162:165], v206 offset:10752
	ds_read_b128 v[158:161], v206 offset:12288
	ds_read_b128 v[154:157], v206 offset:12800
	ds_read_b128 v[150:153], v206 offset:14336
	ds_read_b128 v[146:149], v206 offset:14848
	v_exp_f32_e32 v67, v19
	v_exp_f32_e32 v68, v20
	v_exp_f32_e32 v69, v21
	v_exp_f32_e32 v70, v22
	v_exp_f32_e32 v71, v23
	v_exp_f32_e32 v72, v24
	v_exp_f32_e32 v73, v25
	v_exp_f32_e32 v74, v26
	v_exp_f32_e32 v75, v27
	v_exp_f32_e32 v76, v28
	v_exp_f32_e32 v77, v29
	v_exp_f32_e32 v78, v30
	v_exp_f32_e32 v79, v31
	v_exp_f32_e32 v80, v32
	v_exp_f32_e32 v81, v33
	v_exp_f32_e32 v52, v4
	v_exp_f32_e32 v53, v5
	v_exp_f32_e32 v54, v6
	v_exp_f32_e32 v55, v7
	v_exp_f32_e32 v56, v8
	v_exp_f32_e32 v57, v9
	v_exp_f32_e32 v58, v10
	v_exp_f32_e32 v59, v11
	v_exp_f32_e32 v60, v12
	v_exp_f32_e32 v61, v13
	v_exp_f32_e32 v62, v14
	v_exp_f32_e32 v63, v15
	v_exp_f32_e32 v64, v16
	v_exp_f32_e32 v65, v17
	s_waitcnt vmcnt(2) lgkmcnt(0)
	s_barrier
	v_mov_b32_e32 v2, 0
	v_mov_b32_e32 v3, v224
	v_mov_b32_e32 v4, v224
	v_mov_b32_e32 v5, v224
	v_mov_b32_e32 v6, v224
	v_mov_b32_e32 v7, v224
	v_mov_b32_e32 v8, v224
	v_mov_b32_e32 v9, v224
	v_mov_b32_e32 v10, v224
	v_mov_b32_e32 v11, v224
	v_mov_b32_e32 v12, v224
	v_mov_b32_e32 v13, v224
	v_mov_b32_e32 v14, v224
	v_mov_b32_e32 v15, v224
	v_mov_b32_e32 v16, v224
	v_mov_b32_e32 v17, v224
	v_mov_b32_e32 v18, 0
	v_mov_b32_e32 v19, v224
	v_mov_b32_e32 v20, v224
	v_mov_b32_e32 v21, v224
	v_mov_b32_e32 v22, v224
	v_mov_b32_e32 v23, v224
	v_mov_b32_e32 v24, v224
	v_mov_b32_e32 v25, v224
	v_mov_b32_e32 v26, v224
	v_mov_b32_e32 v27, v224
	v_mov_b32_e32 v28, v224
	v_mov_b32_e32 v29, v224
	v_mov_b32_e32 v30, v224
	v_mov_b32_e32 v31, v224
	v_mov_b32_e32 v32, v224
	v_mov_b32_e32 v33, v224
.LBB0_707:
	s_add_i32 s22, s23, 2
	v_add_u32_e32 v186, s0, v207
	ds_read_b64_tr_b16 v[178:179], v186 offset:24576
	ds_read_b64_tr_b16 v[180:181], v186 offset:25088
	s_waitcnt lgkmcnt(9)
	v_mfma_f32_32x32x16_bf16 v[98:113], v[174:177], v[142:145], v[34:49]
	v_add_f32_e32 v82, v66, v67
	v_add_f32_e32 v82, v68, v82
	v_add_f32_e32 v82, v69, v82
	v_add_f32_e32 v82, v70, v82
	v_add_f32_e32 v82, v71, v82
	v_cvt_pk_bf16_f32 v134, v66, v67
	v_cvt_pk_bf16_f32 v135, v68, v69
	ds_read_b64_tr_b16 v[174:175], v186 offset:28672
	ds_read_b64_tr_b16 v[176:177], v186 offset:29184
	v_add_f32_e32 v66, v72, v82
	s_waitcnt lgkmcnt(10)
	v_mfma_f32_32x32x16_bf16 v[82:97], v[170:173], v[142:145], v[34:49]
	v_add_f32_e32 v66, v73, v66
	v_add_f32_e32 v66, v74, v66
	v_add_f32_e32 v114, v75, v66
	v_cvt_pk_bf16_f32 v136, v70, v71
	v_cvt_pk_bf16_f32 v137, v72, v73
	ds_read_b64_tr_b16 v[66:67], v186 offset:25600
	ds_read_b64_tr_b16 v[68:69], v186 offset:26112
	s_waitcnt lgkmcnt(11)
	v_mfma_f32_32x32x16_bf16 v[98:113], v[166:169], v[138:141], v[98:113]
	v_add_f32_e32 v70, v76, v114
	v_add_f32_e32 v70, v77, v70
	v_add_f32_e32 v70, v78, v70
	v_add_f32_e32 v114, v79, v70
	v_cvt_pk_bf16_f32 v126, v74, v75
	v_cvt_pk_bf16_f32 v127, v76, v77
	ds_read_b64_tr_b16 v[70:71], v186 offset:29696
	ds_read_b64_tr_b16 v[72:73], v186 offset:30208
	s_waitcnt lgkmcnt(12)
	v_mfma_f32_32x32x16_bf16 v[82:97], v[162:165], v[138:141], v[82:97]
	v_add_f32_e32 v74, v80, v114
	v_add_f32_e32 v74, v81, v74
	v_add_f32_e32 v74, v50, v74
	v_add_f32_e32 v114, v51, v74
	v_cvt_pk_bf16_f32 v128, v78, v79
	v_cvt_pk_bf16_f32 v129, v80, v81
	ds_read_b64_tr_b16 v[74:75], v186 offset:26624
	ds_read_b64_tr_b16 v[76:77], v186 offset:27136
	s_waitcnt lgkmcnt(13)
	v_mfma_f32_32x32x16_bf16 v[98:113], v[158:161], v[130:133], v[98:113]
	v_add_f32_e32 v78, v52, v114
	v_add_f32_e32 v78, v53, v78
	v_add_f32_e32 v78, v54, v78
	v_add_f32_e32 v78, v55, v78
	v_cvt_pk_bf16_f32 v118, v50, v51
	v_cvt_pk_bf16_f32 v119, v52, v53
	ds_read_b64_tr_b16 v[50:51], v186 offset:30720
	ds_read_b64_tr_b16 v[52:53], v186 offset:31232
	s_waitcnt lgkmcnt(14)
	v_mfma_f32_32x32x16_bf16 v[82:97], v[154:157], v[130:133], v[82:97]
	v_add_f32_e32 v78, v56, v78
	v_add_f32_e32 v78, v57, v78
	v_add_f32_e32 v78, v58, v78
	v_add_f32_e32 v78, v59, v78
	v_cvt_pk_bf16_f32 v120, v54, v55
	v_cvt_pk_bf16_f32 v121, v56, v57
	ds_read_b64_tr_b16 v[54:55], v186 offset:27648
	ds_read_b64_tr_b16 v[56:57], v186 offset:28160
	s_waitcnt lgkmcnt(14)
	v_mfma_f32_32x32x16_bf16 v[98:113], v[150:153], v[122:125], v[98:113]
	v_add_f32_e32 v78, v60, v78
	v_add_f32_e32 v78, v61, v78
	v_add_f32_e32 v78, v62, v78
	v_add_f32_e32 v78, v63, v78
	v_cvt_pk_bf16_f32 v114, v58, v59
	v_cvt_pk_bf16_f32 v115, v60, v61
	ds_read_b64_tr_b16 v[58:59], v186 offset:31744
	ds_read_b64_tr_b16 v[60:61], v186 offset:32256
	v_mfma_f32_32x32x16_bf16 v[82:97], v[146:149], v[122:125], v[82:97]
	v_add_f32_e32 v78, v64, v78
	v_add_f32_e32 v78, v65, v78
	v_add_f32_e32 v78, 0, v78
	v_cvt_pk_bf16_f32 v116, v62, v63
	v_cvt_pk_bf16_f32 v117, v64, v65
	s_cmpk_gt_u32 s22, 0x7c
	s_cselect_b64 s[0:1], -1, 0
	s_cmpk_lt_u32 s22, 0x7d
	s_cselect_b32 s4, 0, 0xffffff80
	s_cselect_b32 s5, s9, s20
	s_add_i32 s4, s4, s23
	s_lshl_b32 s4, s4, 6
	s_add_i32 s4, s4, s5
	s_addk_i32 s4, 0x140
	v_mad_i64_i32 v[62:63], s[4:5], s4, v217, v[192:193]
	s_add_i32 s4, s24, s18
	s_mov_b32 m0, s4
	s_nop 0
	global_load_lds_dwordx4 v[62:63], off
	v_max_f32_e32 v62, v99, v99
	v_max_f32_e32 v63, v98, v98
	v_max_f32_e32 v62, v63, v62
	v_max3_f32 v63, v100, v101, v83
	v_max3_f32 v62, v62, v82, v84
	v_max3_f32 v62, v62, v85, v102
	v_max3_f32 v63, v63, v104, v105
	v_max3_f32 v62, v62, v103, v86
	v_max3_f32 v63, v63, v88, v89
	v_max3_f32 v62, v62, v87, v106
	v_max3_f32 v63, v63, v108, v109
	v_max3_f32 v62, v62, v107, v90
	v_max3_f32 v63, v63, v92, v93
	v_max3_f32 v62, v62, v91, v110
	v_max3_f32 v63, v63, v112, v113
	v_max3_f32 v62, v62, v111, v94
	v_max3_f32 v63, v63, v96, v97
	v_max3_f32 v62, v62, v95, v63
	v_mov_b32_e32 v63, v62
	s_nop 1
	v_permlane32_swap_b32_e32 v62, v63
	v_max_f32_e32 v63, v63, v63
	v_max_f32_e32 v62, v62, v62
	v_max_f32_e32 v62, v62, v63
	s_add_i32 s4, s21, s19
	s_mov_b32 m0, s4
	s_nop 0
	global_load_lds_dwordx4 v[196:197], off
	v_cmp_lt_f32_e32 vcc, s51, v62
	s_cmp_lg_u64 vcc, 0
	v_add_f32_e32 v224, v224, v78
	s_cselect_b64 s[4:5], -1, 0
	s_cbranch_vccnz .LBB0_715

.LBB0_710:
	s_add_i32 s4, s21, 0x2000
	s_cmpk_lg_i32 s21, 0x4000
	s_cselect_b32 s25, s4, 0
	v_add_u32_e32 v186, s24, v207
	ds_read_b64_tr_b16 v[150:151], v186 offset:24576
	ds_read_b64_tr_b16 v[152:153], v186 offset:25088
	s_waitcnt lgkmcnt(9)
	v_mfma_f32_32x32x16_bf16 v[66:81], v[62:65], v[142:145], v[34:49]
	v_add_f32_e32 v50, v98, v99
	v_add_f32_e32 v50, v100, v50
	v_add_f32_e32 v50, v101, v50
	v_add_f32_e32 v50, v102, v50
	v_add_f32_e32 v50, v103, v50
	v_cvt_pk_bf16_f32 v134, v98, v99
	v_cvt_pk_bf16_f32 v135, v100, v101
	ds_read_b64_tr_b16 v[146:147], v186 offset:28672
	ds_read_b64_tr_b16 v[148:149], v186 offset:29184
	v_add_f32_e32 v50, v104, v50
	v_add_f32_e32 v50, v105, v50
	v_add_f32_e32 v50, v106, v50
	v_add_f32_e32 v114, v107, v50
	s_waitcnt lgkmcnt(10)
	v_mfma_f32_32x32x16_bf16 v[50:65], v[174:177], v[142:145], v[34:49]
	v_cvt_pk_bf16_f32 v136, v102, v103
	v_cvt_pk_bf16_f32 v137, v104, v105
	ds_read_b64_tr_b16 v[98:99], v186 offset:25600
	ds_read_b64_tr_b16 v[100:101], v186 offset:26112
	s_waitcnt lgkmcnt(11)
	v_mfma_f32_32x32x16_bf16 v[66:81], v[178:181], v[138:141], v[66:81]
	v_add_f32_e32 v102, v108, v114
	v_add_f32_e32 v102, v109, v102
	v_add_f32_e32 v102, v110, v102
	v_add_f32_e32 v114, v111, v102
	v_cvt_pk_bf16_f32 v126, v106, v107
	v_cvt_pk_bf16_f32 v127, v108, v109
	ds_read_b64_tr_b16 v[102:103], v186 offset:29696
	ds_read_b64_tr_b16 v[104:105], v186 offset:30208
	s_waitcnt lgkmcnt(12)
	v_mfma_f32_32x32x16_bf16 v[50:65], v[170:173], v[138:141], v[50:65]
	v_add_f32_e32 v106, v112, v114
	v_add_f32_e32 v106, v113, v106
	v_add_f32_e32 v106, v82, v106
	v_add_f32_e32 v114, v83, v106
	v_cvt_pk_bf16_f32 v128, v110, v111
	v_cvt_pk_bf16_f32 v129, v112, v113
	ds_read_b64_tr_b16 v[106:107], v186 offset:26624
	ds_read_b64_tr_b16 v[108:109], v186 offset:27136
	s_waitcnt lgkmcnt(13)
	v_mfma_f32_32x32x16_bf16 v[66:81], v[166:169], v[130:133], v[66:81]
	v_add_f32_e32 v110, v84, v114
	v_add_f32_e32 v110, v85, v110
	v_add_f32_e32 v110, v86, v110
	v_add_f32_e32 v110, v87, v110
	v_cvt_pk_bf16_f32 v118, v82, v83
	v_cvt_pk_bf16_f32 v119, v84, v85
	ds_read_b64_tr_b16 v[82:83], v186 offset:30720
	ds_read_b64_tr_b16 v[84:85], v186 offset:31232
	s_waitcnt lgkmcnt(14)
	v_mfma_f32_32x32x16_bf16 v[50:65], v[162:165], v[130:133], v[50:65]
	v_add_f32_e32 v110, v88, v110
	v_add_f32_e32 v110, v89, v110
	v_add_f32_e32 v110, v90, v110
	v_add_f32_e32 v110, v91, v110
	v_cvt_pk_bf16_f32 v120, v86, v87
	v_cvt_pk_bf16_f32 v121, v88, v89
	ds_read_b64_tr_b16 v[86:87], v186 offset:27648
	ds_read_b64_tr_b16 v[88:89], v186 offset:28160
	s_waitcnt lgkmcnt(14)
	v_mfma_f32_32x32x16_bf16 v[66:81], v[158:161], v[122:125], v[66:81]
	v_add_f32_e32 v110, v92, v110
	v_add_f32_e32 v110, v93, v110
	v_add_f32_e32 v110, v94, v110
	v_add_f32_e32 v110, v95, v110
	v_cvt_pk_bf16_f32 v114, v90, v91
	v_cvt_pk_bf16_f32 v115, v92, v93
	ds_read_b64_tr_b16 v[90:91], v186 offset:31744
	ds_read_b64_tr_b16 v[92:93], v186 offset:32256
	v_mfma_f32_32x32x16_bf16 v[50:65], v[154:157], v[122:125], v[50:65]
	v_add_f32_e32 v110, v96, v110
	v_add_f32_e32 v110, v97, v110
	v_add_f32_e32 v110, 0, v110
	v_cvt_pk_bf16_f32 v116, v94, v95
	v_cvt_pk_bf16_f32 v117, v96, v97
	s_cmpk_lt_u32 s22, 0x7c
	s_cselect_b32 s4, 0, 0xffffff80
	s_cselect_b32 s5, s9, s20
	s_add_i32 s4, s4, s23
	s_lshl_b32 s4, s4, 6
	s_add_i32 s4, s4, s5
	s_addk_i32 s4, 0x180
	v_mad_i64_i32 v[94:95], s[4:5], s4, v217, v[192:193]
	s_add_i32 s4, s21, s18
	s_mov_b32 m0, s4
	s_nop 0
	global_load_lds_dwordx4 v[94:95], off
	v_lshl_add_u64 v[94:95], v[196:197], 0, s[30:31]
	s_add_i32 s4, s25, s19
	s_mov_b32 m0, s4
	s_nop 0
	global_load_lds_dwordx4 v[94:95], off
	v_max_f32_e32 v94, v67, v67
	v_max_f32_e32 v95, v66, v66
	v_max_f32_e32 v94, v95, v94
	v_max3_f32 v95, v68, v69, v51
	v_max3_f32 v94, v94, v50, v52
	v_max3_f32 v94, v94, v53, v70
	v_max3_f32 v95, v95, v72, v73
	v_max3_f32 v94, v94, v71, v54
	v_max3_f32 v95, v95, v56, v57
	v_max3_f32 v94, v94, v55, v74
	v_max3_f32 v95, v95, v76, v77
	v_max3_f32 v94, v94, v75, v58
	v_max3_f32 v95, v95, v60, v61
	v_max3_f32 v94, v94, v59, v78
	v_max3_f32 v95, v95, v80, v81
	v_max3_f32 v94, v94, v79, v62
	v_max3_f32 v95, v95, v64, v65
	v_max3_f32 v94, v94, v63, v95
	v_mov_b32_e32 v95, v94
	s_nop 1
	v_permlane32_swap_b32_e32 v94, v95
	v_max_f32_e32 v95, v95, v95
	v_max_f32_e32 v94, v94, v94
	v_max_f32_e32 v94, v94, v95
	v_cmp_lt_f32_e32 vcc, s51, v94
	s_cmp_lg_u64 vcc, 0
	v_add_f32_e32 v224, v224, v110
	s_cselect_b64 s[4:5], -1, 0
	s_cbranch_vccnz .LBB0_718

.LBB0_722:
	v_add_u32_e32 v186, s0, v207
	ds_read_b64_tr_b16 v[178:179], v186 offset:24576
	ds_read_b64_tr_b16 v[180:181], v186 offset:25088
	s_waitcnt lgkmcnt(9)
	v_mfma_f32_32x32x16_bf16 v[98:113], v[174:177], v[142:145], v[34:49]
	v_add_f32_e32 v82, v66, v67
	v_add_f32_e32 v82, v68, v82
	v_add_f32_e32 v82, v69, v82
	v_add_f32_e32 v82, v70, v82
	v_add_f32_e32 v82, v71, v82
	v_cvt_pk_bf16_f32 v134, v66, v67
	v_cvt_pk_bf16_f32 v135, v68, v69
	ds_read_b64_tr_b16 v[174:175], v186 offset:28672
	ds_read_b64_tr_b16 v[176:177], v186 offset:29184
	v_add_f32_e32 v66, v72, v82
	s_waitcnt lgkmcnt(10)
	v_mfma_f32_32x32x16_bf16 v[82:97], v[170:173], v[142:145], v[34:49]
	v_add_f32_e32 v66, v73, v66
	v_add_f32_e32 v66, v74, v66
	v_add_f32_e32 v114, v75, v66
	v_cvt_pk_bf16_f32 v136, v70, v71
	v_cvt_pk_bf16_f32 v137, v72, v73
	ds_read_b64_tr_b16 v[66:67], v186 offset:25600
	ds_read_b64_tr_b16 v[68:69], v186 offset:26112
	s_waitcnt lgkmcnt(11)
	v_mfma_f32_32x32x16_bf16 v[98:113], v[166:169], v[138:141], v[98:113]
	v_add_f32_e32 v70, v76, v114
	v_add_f32_e32 v70, v77, v70
	v_add_f32_e32 v70, v78, v70
	v_add_f32_e32 v114, v79, v70
	v_cvt_pk_bf16_f32 v126, v74, v75
	v_cvt_pk_bf16_f32 v127, v76, v77
	ds_read_b64_tr_b16 v[70:71], v186 offset:29696
	ds_read_b64_tr_b16 v[72:73], v186 offset:30208
	s_waitcnt lgkmcnt(12)
	v_mfma_f32_32x32x16_bf16 v[82:97], v[162:165], v[138:141], v[82:97]
	v_add_f32_e32 v74, v80, v114
	v_add_f32_e32 v74, v81, v74
	v_add_f32_e32 v74, v50, v74
	v_add_f32_e32 v114, v51, v74
	v_cvt_pk_bf16_f32 v128, v78, v79
	v_cvt_pk_bf16_f32 v129, v80, v81
	ds_read_b64_tr_b16 v[74:75], v186 offset:26624
	ds_read_b64_tr_b16 v[76:77], v186 offset:27136
	s_waitcnt lgkmcnt(13)
	v_mfma_f32_32x32x16_bf16 v[98:113], v[158:161], v[130:133], v[98:113]
	v_add_f32_e32 v78, v52, v114
	v_add_f32_e32 v78, v53, v78
	v_add_f32_e32 v78, v54, v78
	v_add_f32_e32 v78, v55, v78
	v_cvt_pk_bf16_f32 v118, v50, v51
	v_cvt_pk_bf16_f32 v119, v52, v53
	ds_read_b64_tr_b16 v[50:51], v186 offset:30720
	ds_read_b64_tr_b16 v[52:53], v186 offset:31232
	s_waitcnt lgkmcnt(14)
	v_mfma_f32_32x32x16_bf16 v[82:97], v[154:157], v[130:133], v[82:97]
	v_add_f32_e32 v78, v56, v78
	v_add_f32_e32 v78, v57, v78
	v_add_f32_e32 v78, v58, v78
	v_add_f32_e32 v78, v59, v78
	v_cvt_pk_bf16_f32 v120, v54, v55
	v_cvt_pk_bf16_f32 v121, v56, v57
	ds_read_b64_tr_b16 v[54:55], v186 offset:27648
	ds_read_b64_tr_b16 v[56:57], v186 offset:28160
	s_waitcnt lgkmcnt(14)
	v_mfma_f32_32x32x16_bf16 v[98:113], v[150:153], v[122:125], v[98:113]
	v_add_f32_e32 v78, v60, v78
	v_add_f32_e32 v78, v61, v78
	v_add_f32_e32 v78, v62, v78
	v_add_f32_e32 v78, v63, v78
	v_cvt_pk_bf16_f32 v114, v58, v59
	v_cvt_pk_bf16_f32 v115, v60, v61
	ds_read_b64_tr_b16 v[58:59], v186 offset:31744
	ds_read_b64_tr_b16 v[60:61], v186 offset:32256
	v_mfma_f32_32x32x16_bf16 v[82:97], v[146:149], v[122:125], v[82:97]
	v_add_f32_e32 v78, v64, v78
	v_add_f32_e32 v78, v65, v78
	v_add_f32_e32 v78, 0, v78
	v_cvt_pk_bf16_f32 v116, v62, v63
	v_cvt_pk_bf16_f32 v117, v64, v65
	s_cmpk_gt_u32 s21, 0x80
	s_cselect_b64 s[0:1], -1, 0
	s_and_b64 vcc, exec, s[0:1]
	s_cbranch_vccnz .LBB0_724
	s_sub_i32 s4, s20, 64
	v_mad_i64_i32 v[62:63], s[4:5], s4, v217, v[192:193]
	s_add_i32 s4, s23, s18
	s_mov_b32 m0, s4
	s_nop 0
	global_load_lds_dwordx4 v[62:63], off
.LBB0_724:
	v_max_f32_e32 v62, v99, v99
	v_max_f32_e32 v63, v98, v98
	v_max_f32_e32 v62, v63, v62
	v_max3_f32 v63, v100, v101, v83
	v_max3_f32 v62, v62, v82, v84
	v_max3_f32 v62, v62, v85, v102
	v_max3_f32 v63, v63, v104, v105
	v_max3_f32 v62, v62, v103, v86
	v_max3_f32 v63, v63, v88, v89
	v_max3_f32 v62, v62, v87, v106
	v_max3_f32 v63, v63, v108, v109
	v_max3_f32 v62, v62, v107, v90
	v_max3_f32 v63, v63, v92, v93
	v_max3_f32 v62, v62, v91, v110
	v_max3_f32 v63, v63, v112, v113
	v_max3_f32 v62, v62, v111, v94
	v_max3_f32 v63, v63, v96, v97
	v_max3_f32 v62, v62, v95, v63
	v_mov_b32_e32 v63, v62
	s_nop 1
	v_permlane32_swap_b32_e32 v62, v63
	v_max_f32_e32 v63, v63, v63
	v_max_f32_e32 v62, v62, v62
	v_max_f32_e32 v62, v62, v63
	s_add_i32 s4, s22, s19
	s_mov_b32 m0, s4
	s_nop 0
	global_load_lds_dwordx4 v[194:195], off
	v_cmp_lt_f32_e32 vcc, s51, v62
	s_cmp_lg_u64 vcc, 0
	v_add_f32_e32 v196, v224, v78
	s_cselect_b64 s[4:5], -1, 0
	s_cbranch_vccnz .LBB0_750

.LBB0_733:
	v_add_u32_e32 v186, s23, v207
	ds_read_b64_tr_b16 v[154:155], v186 offset:24576
	ds_read_b64_tr_b16 v[156:157], v186 offset:25088
	s_waitcnt lgkmcnt(9)
	v_mfma_f32_32x32x16_bf16 v[66:81], v[62:65], v[142:145], v[34:49]
	v_add_f32_e32 v50, v98, v99
	v_add_f32_e32 v50, v100, v50
	v_add_f32_e32 v50, v101, v50
	v_add_f32_e32 v50, v102, v50
	v_add_f32_e32 v50, v103, v50
	v_cvt_pk_bf16_f32 v134, v98, v99
	v_cvt_pk_bf16_f32 v135, v100, v101
	ds_read_b64_tr_b16 v[150:151], v186 offset:28672
	ds_read_b64_tr_b16 v[152:153], v186 offset:29184
	v_add_f32_e32 v50, v104, v50
	v_add_f32_e32 v50, v105, v50
	v_add_f32_e32 v50, v106, v50
	v_add_f32_e32 v114, v107, v50
	s_waitcnt lgkmcnt(10)
	v_mfma_f32_32x32x16_bf16 v[50:65], v[174:177], v[142:145], v[34:49]
	v_cvt_pk_bf16_f32 v136, v102, v103
	v_cvt_pk_bf16_f32 v137, v104, v105
	ds_read_b64_tr_b16 v[98:99], v186 offset:25600
	ds_read_b64_tr_b16 v[100:101], v186 offset:26112
	s_waitcnt lgkmcnt(11)
	v_mfma_f32_32x32x16_bf16 v[66:81], v[178:181], v[138:141], v[66:81]
	v_add_f32_e32 v102, v108, v114
	v_add_f32_e32 v102, v109, v102
	v_add_f32_e32 v102, v110, v102
	v_add_f32_e32 v114, v111, v102
	v_cvt_pk_bf16_f32 v126, v106, v107
	v_cvt_pk_bf16_f32 v127, v108, v109
	ds_read_b64_tr_b16 v[102:103], v186 offset:29696
	ds_read_b64_tr_b16 v[104:105], v186 offset:30208
	s_waitcnt lgkmcnt(12)
	v_mfma_f32_32x32x16_bf16 v[50:65], v[170:173], v[138:141], v[50:65]
	v_add_f32_e32 v106, v112, v114
	v_add_f32_e32 v106, v113, v106
	v_add_f32_e32 v106, v82, v106
	v_add_f32_e32 v114, v83, v106
	v_cvt_pk_bf16_f32 v128, v110, v111
	v_cvt_pk_bf16_f32 v129, v112, v113
	ds_read_b64_tr_b16 v[106:107], v186 offset:26624
	ds_read_b64_tr_b16 v[108:109], v186 offset:27136
	s_waitcnt lgkmcnt(13)
	v_mfma_f32_32x32x16_bf16 v[66:81], v[166:169], v[130:133], v[66:81]
	v_add_f32_e32 v110, v84, v114
	v_add_f32_e32 v110, v85, v110
	v_add_f32_e32 v110, v86, v110
	v_add_f32_e32 v110, v87, v110
	v_cvt_pk_bf16_f32 v118, v82, v83
	v_cvt_pk_bf16_f32 v119, v84, v85
	ds_read_b64_tr_b16 v[82:83], v186 offset:30720
	ds_read_b64_tr_b16 v[84:85], v186 offset:31232
	s_waitcnt lgkmcnt(14)
	v_mfma_f32_32x32x16_bf16 v[50:65], v[162:165], v[130:133], v[50:65]
	v_add_f32_e32 v110, v88, v110
	v_add_f32_e32 v110, v89, v110
	v_add_f32_e32 v110, v90, v110
	v_add_f32_e32 v110, v91, v110
	v_cvt_pk_bf16_f32 v120, v86, v87
	v_cvt_pk_bf16_f32 v121, v88, v89
	ds_read_b64_tr_b16 v[86:87], v186 offset:27648
	ds_read_b64_tr_b16 v[88:89], v186 offset:28160
	s_waitcnt lgkmcnt(14)
	v_mfma_f32_32x32x16_bf16 v[66:81], v[158:161], v[122:125], v[66:81]
	v_add_f32_e32 v110, v92, v110
	v_add_f32_e32 v110, v93, v110
	v_add_f32_e32 v110, v94, v110
	v_add_f32_e32 v110, v95, v110
	v_cvt_pk_bf16_f32 v114, v90, v91
	v_cvt_pk_bf16_f32 v115, v92, v93
	ds_read_b64_tr_b16 v[90:91], v186 offset:31744
	ds_read_b64_tr_b16 v[92:93], v186 offset:32256
	v_mfma_f32_32x32x16_bf16 v[50:65], v[146:149], v[122:125], v[50:65]
	v_add_f32_e32 v110, v96, v110
	v_add_f32_e32 v110, v97, v110
	v_add_f32_e32 v110, 0, v110
	v_cvt_pk_bf16_f32 v116, v94, v95
	v_cvt_pk_bf16_f32 v117, v96, v97
	s_cmpk_gt_u32 s21, 0x7f
	s_cselect_b64 s[4:5], -1, 0
	s_and_b64 vcc, exec, s[4:5]
	s_cbranch_vccnz .LBB0_735
	v_mad_i64_i32 v[94:95], s[6:7], s20, v217, v[192:193]
	s_add_i32 s6, s22, s18
	s_mov_b32 m0, s6
	s_nop 0
	global_load_lds_dwordx4 v[94:95], off
.LBB0_735:
	s_add_i32 s6, s22, 0x2000
	s_cmpk_lg_i32 s22, 0x4000
	s_cselect_b32 s23, s6, 0
	v_lshl_add_u64 v[94:95], v[194:195], 0, s[30:31]
	s_add_i32 s6, s23, s19
	s_mov_b32 m0, s6
	s_nop 0
	global_load_lds_dwordx4 v[94:95], off
	v_max_f32_e32 v94, v67, v67
	v_max_f32_e32 v95, v66, v66
	v_max_f32_e32 v94, v95, v94
	v_max3_f32 v95, v68, v69, v51
	v_max3_f32 v94, v94, v50, v52
	v_max3_f32 v94, v94, v53, v70
	v_max3_f32 v95, v95, v72, v73
	v_max3_f32 v94, v94, v71, v54
	v_max3_f32 v95, v95, v56, v57
	v_max3_f32 v94, v94, v55, v74
	v_max3_f32 v95, v95, v76, v77
	v_max3_f32 v94, v94, v75, v58
	v_max3_f32 v95, v95, v60, v61
	v_max3_f32 v94, v94, v59, v78
	v_max3_f32 v95, v95, v80, v81
	v_max3_f32 v94, v94, v79, v62
	v_max3_f32 v95, v95, v64, v65
	v_max3_f32 v94, v94, v63, v95
	v_mov_b32_e32 v95, v94
	s_nop 1
	v_permlane32_swap_b32_e32 v94, v95
	v_max_f32_e32 v95, v95, v95
	v_max_f32_e32 v94, v94, v94
	v_max_f32_e32 v94, v94, v95
	v_cmp_lt_f32_e32 vcc, s51, v94
	s_cmp_lg_u64 vcc, 0
	v_add_f32_e32 v224, v196, v110
	s_cselect_b64 s[6:7], -1, 0
	s_cbranch_vccnz .LBB0_753

.LBB0_891:
	s_sext_i32_i8 s11, s3
	s_lshl_b32 s12, s11, 8
	s_add_i32 s18, s12, 0x4000
	s_add_i32 s3, s9, 0x280
	s_and_b64 s[0:1], exec, s[0:1]
	s_cselect_b32 s0, s9, s3
	s_mul_i32 s3, s18, 0xe00
	v_readlane_b32 s14, v254, 35
	s_mul_hi_u32 s1, s18, 0xe00
	v_readlane_b32 s15, v254, 36
	s_add_u32 s3, s14, s3
	s_addc_u32 s5, s15, s1
	s_ashr_i32 s1, s0, 31
	s_lshl_b64 s[0:1], s[0:1], 1
	s_add_u32 s10, s3, s0
	s_mov_b32 s3, s19
	s_addc_u32 s13, s5, s1
	s_lshl_b64 s[0:1], s[2:3], 1
	s_add_u32 s0, s14, s0
	s_mov_b32 s5, s19
	s_addc_u32 s1, s15, s1
	s_lshl_b64 s[2:3], s[4:5], 1
	s_add_u32 s14, s14, s2
	v_mov_b32_e32 v36, v191
	s_addc_u32 s15, s15, s3
	v_mov_b32_e32 v4, v1
	v_readfirstlane_b32 s3, v36
	v_and_b32_e32 v189, 63, v36
	s_ashr_i32 s7, s3, 6
	s_lshl_b32 s2, s7, 5
	s_mul_i32 s4, s7, 0x1c000
	v_mul_u32_u24_e32 v0, 0x700, v189
	s_mul_hi_i32 s5, s2, 0xe00
	s_add_u32 s16, s10, s4
	v_lshlrev_b32_e32 v0, 1, v0
	s_addc_u32 s17, s13, s5
	v_lshl_add_u64 v[2:3], s[0:1], 0, v[0:1]
	s_lshl_b32 s0, s7, 3
	s_ashr_i32 s1, s0, 31
	v_lshl_add_u64 v[34:35], s[0:1], 1, v[2:3]
	s_lshl_b32 s0, s7, 4
	v_bfe_u32 v0, v36, 2, 4
	v_and_or_b32 v0, s0, 48, v0
	v_mul_u32_u24_e32 v0, 0x700, v0
	s_ashr_i32 s0, s3, 3
	v_lshlrev_b32_e32 v0, 1, v0
	s_andn2_b32 s0, s0, 31
	v_lshl_add_u64 v[2:3], s[14:15], 0, v[0:1]
	s_ashr_i32 s1, s0, 31
	s_and_b32 s4, s3, 0x3fffffc0
	v_lshl_add_u64 v[2:3], s[0:1], 1, v[2:3]
	v_lshlrev_b32_e32 v194, 3, v36
	s_lshl_b32 s0, s7, 10
	v_and_b32_e32 v197, 24, v194
	s_cmp_lg_u32 0, -1
	v_lshlrev_b32_e32 v0, 1, v197
	s_cselect_b32 s1, 0, 0
	v_and_b32_e32 v195, 31, v36
	v_lshl_add_u64 v[38:39], v[2:3], 0, v[0:1]
	s_add_i32 s0, s1, s0
	v_mad_u64_u32 v[2:3], s[14:15], s18, v217, v[34:35]
	s_mov_b32 m0, s0
	s_nop 0
	global_load_lds_dwordx4 v[2:3], off
	s_add_i32 s3, s0, 0x6000
	v_mad_u64_u32 v[2:3], s[14:15], s18, v217, v[38:39]
	s_mov_b32 m0, s3
	s_nop 0
	global_load_lds_dwordx4 v[2:3], off
	v_mul_u32_u24_e32 v0, 0x700, v195
	v_bfe_u32 v196, v36, 5, 1
	s_add_i32 s1, s12, 0x4040
	v_lshlrev_b32_e32 v0, 1, v0
	v_mad_u64_u32 v[2:3], s[14:15], s1, v217, v[34:35]
	s_add_i32 s5, s0, 0x2000
	s_mov_b32 m0, s5
	s_nop 0
	global_load_lds_dwordx4 v[2:3], off
	v_lshl_or_b32 v0, v196, 4, v0
	global_load_dwordx4 v[142:145], v0, s[16:17]
	global_load_dwordx4 v[138:141], v0, s[16:17] offset:32
	global_load_dwordx4 v[130:133], v0, s[16:17] offset:64
	global_load_dwordx4 v[114:117], v0, s[16:17] offset:96
	v_lshlrev_b32_e32 v2, 4, v195
	v_lshl_add_u32 v0, v196, 10, 0
	v_add_u32_e32 v203, v0, v2
	v_mov_b32_e32 v2, v1
	v_mov_b32_e32 v3, v1
	v_mov_b32_e32 v5, v1
	v_mov_b32_e32 v6, v1
	v_mov_b32_e32 v7, v1
	v_mov_b32_e32 v8, v1
	v_mov_b32_e32 v9, v1
	v_mov_b32_e32 v10, v1
	v_mov_b32_e32 v11, v1
	v_mov_b32_e32 v12, v1
	v_mov_b32_e32 v13, v1
	v_mov_b32_e32 v14, v1
	v_mov_b32_e32 v15, v1
	v_mov_b32_e32 v0, v1
	v_mov_b64_e32 v[16:17], v[14:15]
	v_mov_b64_e32 v[14:15], v[12:13]
	v_mov_b64_e32 v[12:13], v[10:11]
	v_mov_b64_e32 v[10:11], v[8:9]
	v_mov_b64_e32 v[8:9], v[6:7]
	v_mov_b64_e32 v[6:7], v[4:5]
	v_mov_b64_e32 v[4:5], v[2:3]
	v_mov_b64_e32 v[2:3], v[0:1]
	s_add_i32 s5, s12, 0x4080
	v_mad_u64_u32 v[18:19], s[14:15], s5, v217, v[34:35]
	s_add_i32 s5, s0, 0x4000
	s_mov_b32 m0, s5
	s_nop 0
	global_load_lds_dwordx4 v[18:19], off
	s_waitcnt vmcnt(3) lgkmcnt(0)
	s_barrier
	ds_read_b128 v[40:43], v203
	ds_read_b128 v[44:47], v203 offset:512
	s_waitcnt vmcnt(3) lgkmcnt(1)
	v_mfma_f32_32x32x16_bf16 v[18:33], v[40:43], v[142:145], v[2:17]
	s_lshl_b32 s4, s4, 2
	s_addk_i32 s12, 0x40c0
	s_add_i32 s10, s4, 0
	v_lshlrev_b32_e32 v0, 1, v36
	v_lshlrev_b32_e32 v36, 4, v36
	v_and_b32_e32 v0, 32, v0
	v_and_b32_e32 v36, 0xc0, v36
	s_waitcnt lgkmcnt(0)
	v_mfma_f32_32x32x16_bf16 v[2:17], v[44:47], v[142:145], v[2:17]
	ds_read_b128 v[40:43], v203 offset:2048
	ds_read_b128 v[44:47], v203 offset:2560
	v_lshl_or_b32 v198, v196, 8, v36
	v_add3_u32 v36, 0, v0, v197
	v_add_u32_e32 v202, v36, v198
	v_cmp_gt_u32_e64 s[40:41], 32, v189
	v_lshl_add_u32 v199, v195, 2, s10
	s_waitcnt vmcnt(2) lgkmcnt(1)
	v_mfma_f32_32x32x16_bf16 v[18:33], v[40:43], v[138:141], v[18:33]
	s_waitcnt lgkmcnt(0)
	v_mfma_f32_32x32x16_bf16 v[2:17], v[44:47], v[138:141], v[2:17]
	ds_read_b128 v[40:43], v203 offset:4096
	ds_read_b128 v[44:47], v203 offset:4608
	s_waitcnt vmcnt(1) lgkmcnt(1)
	v_mfma_f32_32x32x16_bf16 v[18:33], v[40:43], v[130:133], v[18:33]
	s_waitcnt lgkmcnt(0)
	v_mfma_f32_32x32x16_bf16 v[2:17], v[44:47], v[130:133], v[2:17]
	ds_read_b128 v[40:43], v203 offset:6144
	ds_read_b128 v[44:47], v203 offset:6656
	s_waitcnt vmcnt(0) lgkmcnt(1)
	v_mfma_f32_32x32x16_bf16 v[18:33], v[40:43], v[114:117], v[18:33]
	s_waitcnt lgkmcnt(0)
	v_mfma_f32_32x32x16_bf16 v[2:17], v[44:47], v[114:117], v[2:17]
	s_nop 15
	s_nop 7
	s_nop 0
	v_max3_f32 v37, v18, v19, v2
	v_max3_f32 v40, v20, v21, v3
	s_nop 0
	v_max3_f32 v37, v37, v4, v5
	v_max3_f32 v40, v40, v24, v25
	s_nop 0
	v_max3_f32 v37, v37, v22, v23
	v_max3_f32 v40, v40, v8, v9
	s_nop 0
	v_max3_f32 v37, v37, v6, v7
	v_max3_f32 v40, v40, v28, v29
	s_nop 0
	v_max3_f32 v37, v37, v26, v27
	v_max3_f32 v40, v40, v12, v13
	s_nop 0
	v_max3_f32 v37, v37, v10, v11
	v_max3_f32 v40, v40, v32, v33
	s_nop 0
	v_max3_f32 v37, v37, v30, v31
	v_max3_f32 v40, v40, v16, v17
	s_nop 0
	v_max3_f32 v37, v37, v14, v15
	s_nop 0
	v_max_f32_e32 v37, v37, v40
	s_nop 0
	v_mov_b32_e32 v40, v37
	s_nop 1
	v_permlane32_swap_b32_e32 v37, v40
	v_max_f32_e32 v37, v37, v40
	s_nop 0
	v_add_f32_e32 v200, v1, v37
	v_sub_f32_e32 v40, v2, v37
	v_sub_f32_e32 v18, v18, v37
	v_sub_f32_e32 v19, v19, v37
	v_sub_f32_e32 v41, v3, v37
	v_sub_f32_e32 v20, v20, v37
	s_nop 0
	v_xor_b32_e32 v2, 0x80000000, v200
	v_sub_f32_e32 v42, v4, v37
	v_sub_f32_e32 v21, v21, v37
	v_sub_f32_e32 v43, v5, v37
	v_sub_f32_e32 v22, v22, v37
	v_sub_f32_e32 v44, v6, v37
	v_sub_f32_e32 v23, v23, v37
	v_sub_f32_e32 v45, v7, v37
	v_sub_f32_e32 v24, v24, v37
	v_sub_f32_e32 v46, v8, v37
	v_sub_f32_e32 v25, v25, v37
	v_sub_f32_e32 v47, v9, v37
	v_sub_f32_e32 v26, v26, v37
	v_sub_f32_e32 v48, v10, v37
	v_sub_f32_e32 v27, v27, v37
	v_sub_f32_e32 v49, v11, v37
	v_sub_f32_e32 v28, v28, v37
	v_sub_f32_e32 v50, v12, v37
	v_sub_f32_e32 v29, v29, v37
	v_sub_f32_e32 v51, v13, v37
	v_sub_f32_e32 v30, v30, v37
	v_sub_f32_e32 v52, v14, v37
	v_sub_f32_e32 v31, v31, v37
	v_sub_f32_e32 v53, v15, v37
	v_sub_f32_e32 v32, v32, v37
	v_sub_f32_e32 v54, v16, v37
	v_sub_f32_e32 v33, v33, v37
	v_sub_f32_e32 v37, v17, v37
	v_mov_b32_e32 v3, v2
	v_mov_b32_e32 v4, v2
	v_mov_b32_e32 v5, v2
	v_mov_b32_e32 v6, v2
	v_mov_b32_e32 v7, v2
	v_mov_b32_e32 v8, v2
	v_mov_b32_e32 v9, v2
	v_mov_b32_e32 v10, v2
	v_mov_b32_e32 v11, v2
	v_mov_b32_e32 v12, v2
	v_mov_b32_e32 v13, v2
	v_mov_b32_e32 v14, v2
	v_mov_b32_e32 v15, v2
	v_mov_b32_e32 v16, v2
	v_mov_b32_e32 v17, v2
	s_waitcnt vmcnt(0) lgkmcnt(0)
	s_barrier
	v_exp_f32_e32 v55, v18
	v_exp_f32_e32 v56, v19
	v_mad_u64_u32 v[18:19], s[4:5], s12, v217, v[34:35]
	s_mov_b32 m0, s0
	s_nop 0
	global_load_lds_dwordx4 v[18:19], off
	v_exp_f32_e32 v59, v22
	v_mad_u64_u32 v[18:19], s[4:5], s1, v217, v[38:39]
	s_add_i32 s1, s0, 0x8000
	s_mov_b32 m0, s1
	s_nop 0
	global_load_lds_dwordx4 v[18:19], off
	v_exp_f32_e32 v60, v23
	v_exp_f32_e32 v61, v24
	v_exp_f32_e32 v62, v25
	v_exp_f32_e32 v63, v26
	v_exp_f32_e32 v64, v27
	v_exp_f32_e32 v65, v28
	v_exp_f32_e32 v94, v29
	v_exp_f32_e32 v95, v30
	v_exp_f32_e32 v96, v31
	v_exp_f32_e32 v97, v32
	v_exp_f32_e32 v126, v33
	v_exp_f32_e32 v127, v40
	v_exp_f32_e32 v128, v41
	v_exp_f32_e32 v129, v42
	v_exp_f32_e32 v134, v43
	v_exp_f32_e32 v135, v44
	v_exp_f32_e32 v136, v45
	v_exp_f32_e32 v137, v46
	v_exp_f32_e32 v146, v47
	ds_read_b128 v[22:25], v203 offset:8192
	ds_read_b128 v[26:29], v203 offset:8704
	ds_read_b128 v[30:33], v203 offset:10240
	ds_read_b128 v[40:43], v203 offset:10752
	ds_read_b128 v[44:47], v203 offset:12288
	ds_read_b128 v[82:85], v203 offset:12800
	ds_read_b128 v[86:89], v203 offset:14336
	ds_read_b128 v[90:93], v203 offset:14848
	v_exp_f32_e32 v57, v20
	v_exp_f32_e32 v58, v21
	s_waitcnt vmcnt(2) lgkmcnt(0)
	s_barrier
	v_exp_f32_e32 v48, v48
	v_exp_f32_e32 v49, v49
	v_exp_f32_e32 v147, v50
	v_exp_f32_e32 v148, v51
	v_exp_f32_e32 v149, v52
	v_exp_f32_e32 v150, v53
	v_exp_f32_e32 v151, v54
	v_exp_f32_e32 v152, v37
	ds_read_b64_tr_b16 v[18:19], v202 offset:24576
	ds_read_b64_tr_b16 v[20:21], v202 offset:25088
	s_waitcnt lgkmcnt(9)
	v_mfma_f32_32x32x16_bf16 v[98:113], v[22:25], v[142:145], v[2:17]
	v_add_f32_e32 v34, v55, v56
	v_add_f32_e32 v34, v34, v57
	v_add_f32_e32 v34, v34, v58
	v_add_f32_e32 v34, v34, v59
	v_add_f32_e32 v50, v34, v60
	v_cvt_pk_bf16_f32 v122, v55, v56
	v_cvt_pk_bf16_f32 v123, v57, v58
	ds_read_b64_tr_b16 v[34:35], v202 offset:28672
	ds_read_b64_tr_b16 v[36:37], v202 offset:29184
	s_waitcnt lgkmcnt(10)
	v_mfma_f32_32x32x16_bf16 v[66:81], v[26:29], v[142:145], v[2:17]
	v_add_f32_e32 v22, v61, v50
	v_add_f32_e32 v22, v62, v22
	v_add_f32_e32 v22, v63, v22
	v_add_f32_e32 v22, v64, v22
	v_cvt_pk_bf16_f32 v124, v59, v60
	v_cvt_pk_bf16_f32 v125, v61, v62
	ds_read_b64_tr_b16 v[50:51], v202 offset:25600
	ds_read_b64_tr_b16 v[52:53], v202 offset:26112
	s_waitcnt lgkmcnt(11)
	v_mfma_f32_32x32x16_bf16 v[98:113], v[30:33], v[138:141], v[98:113]
	v_add_f32_e32 v22, v65, v22
	v_add_f32_e32 v22, v94, v22
	v_add_f32_e32 v22, v95, v22
	v_add_f32_e32 v22, v96, v22
	v_cvt_pk_bf16_f32 v118, v63, v64
	v_cvt_pk_bf16_f32 v119, v65, v94
	ds_read_b64_tr_b16 v[54:55], v202 offset:29696
	ds_read_b64_tr_b16 v[56:57], v202 offset:30208
	s_waitcnt lgkmcnt(12)
	v_mfma_f32_32x32x16_bf16 v[66:81], v[40:43], v[138:141], v[66:81]
	v_add_f32_e32 v22, v97, v22
	v_add_f32_e32 v22, v126, v22
	v_add_f32_e32 v22, v127, v22
	v_add_f32_e32 v22, v128, v22
	v_cvt_pk_bf16_f32 v120, v95, v96
	v_cvt_pk_bf16_f32 v121, v97, v126
	ds_read_b64_tr_b16 v[58:59], v202 offset:26624
	ds_read_b64_tr_b16 v[60:61], v202 offset:27136
	s_waitcnt lgkmcnt(13)
	v_mfma_f32_32x32x16_bf16 v[98:113], v[44:47], v[130:133], v[98:113]
	v_add_f32_e32 v22, v129, v22
	v_add_f32_e32 v22, v134, v22
	v_add_f32_e32 v22, v135, v22
	v_add_f32_e32 v22, v136, v22
	v_cvt_pk_bf16_f32 v126, v127, v128
	v_cvt_pk_bf16_f32 v127, v129, v134
	ds_read_b64_tr_b16 v[62:63], v202 offset:30720
	ds_read_b64_tr_b16 v[64:65], v202 offset:31232
	s_waitcnt lgkmcnt(14)
	v_mfma_f32_32x32x16_bf16 v[66:81], v[82:85], v[130:133], v[66:81]
	v_add_f32_e32 v22, v137, v22
	v_add_f32_e32 v22, v146, v22
	v_add_f32_e32 v22, v48, v22
	v_add_f32_e32 v22, v49, v22
	v_cvt_pk_bf16_f32 v128, v135, v136
	v_cvt_pk_bf16_f32 v129, v137, v146
	ds_read_b64_tr_b16 v[82:83], v202 offset:27648
	ds_read_b64_tr_b16 v[84:85], v202 offset:28160
	s_waitcnt lgkmcnt(14)
	v_mfma_f32_32x32x16_bf16 v[98:113], v[86:89], v[114:117], v[98:113]
	v_add_f32_e32 v22, v147, v22
	v_add_f32_e32 v22, v148, v22
	v_add_f32_e32 v22, v149, v22
	v_add_f32_e32 v22, v150, v22
	v_cvt_pk_bf16_f32 v134, v48, v49
	v_cvt_pk_bf16_f32 v135, v147, v148
	ds_read_b64_tr_b16 v[86:87], v202 offset:31744
	ds_read_b64_tr_b16 v[88:89], v202 offset:32256
	v_mfma_f32_32x32x16_bf16 v[66:81], v[90:93], v[114:117], v[66:81]
	v_add_f32_e32 v22, v151, v22
	v_add_f32_e32 v22, v152, v22
	v_add_f32_e32 v22, 0, v22
	v_cvt_pk_bf16_f32 v136, v149, v150
	v_cvt_pk_bf16_f32 v137, v151, v152
	s_mul_i32 s4, s11, 0xe0000
	s_ashr_i32 s5, s4, 31
	v_lshl_add_u64 v[192:193], v[38:39], 0, s[4:5]
	s_mov_b64 s[4:5], 0x3870000
	v_add_f32_e32 v204, 0, v22
	v_lshl_add_u64 v[22:23], v[192:193], 0, s[4:5]
	s_add_i32 s0, s0, 0xa000
	s_mov_b32 m0, s0
	s_nop 0
	global_load_lds_dwordx4 v[22:23], off
	v_max_f32_e32 v22, v99, v99
	v_max_f32_e32 v23, v98, v98
	v_max_f32_e32 v22, v23, v22
	v_max3_f32 v23, v100, v101, v67
	v_max3_f32 v22, v22, v66, v68
	v_max3_f32 v22, v22, v69, v102
	v_max3_f32 v23, v23, v104, v105
	v_max3_f32 v22, v22, v103, v70
	v_max3_f32 v23, v23, v72, v73
	v_max3_f32 v22, v22, v71, v106
	v_max3_f32 v23, v23, v108, v109
	v_max3_f32 v22, v22, v107, v74
	v_max3_f32 v23, v23, v76, v77
	v_max3_f32 v22, v22, v75, v110
	v_max3_f32 v23, v23, v112, v113
	v_max3_f32 v22, v22, v111, v78
	v_max3_f32 v23, v23, v80, v81
	v_max3_f32 v22, v22, v79, v23
	v_mov_b32_e32 v23, v22
	s_nop 1
	v_permlane32_swap_b32_e32 v22, v23
	v_max_f32_e32 v23, v23, v23
	v_max_f32_e32 v22, v22, v22
	v_max_f32_e32 v22, v22, v23
	v_cmp_lt_f32_e32 vcc, s51, v22
	s_cmp_lg_u64 vcc, 0
	s_cselect_b64 s[0:1], -1, 0
	s_cbranch_vccnz .LBB0_902

.LBB0_894:
	ds_read_b64_tr_b16 v[150:151], v202 offset:32768
	ds_read_b64_tr_b16 v[152:153], v202 offset:33280
	s_waitcnt lgkmcnt(9)
	v_mfma_f32_32x32x16_bf16 v[82:97], v[146:149], v[142:145], v[2:17]
	v_add_f32_e32 v50, v98, v99
	v_add_f32_e32 v50, v100, v50
	v_add_f32_e32 v50, v101, v50
	v_add_f32_e32 v50, v102, v50
	v_add_f32_e32 v50, v103, v50
	v_cvt_pk_bf16_f32 v122, v98, v99
	v_cvt_pk_bf16_f32 v123, v100, v101
	ds_read_b64_tr_b16 v[146:147], v202 offset:36864
	ds_read_b64_tr_b16 v[148:149], v202 offset:37376
	v_add_f32_e32 v50, v104, v50
	v_add_f32_e32 v50, v105, v50
	v_add_f32_e32 v50, v106, v50
	v_add_f32_e32 v118, v107, v50
	s_waitcnt lgkmcnt(10)
	v_mfma_f32_32x32x16_bf16 v[50:65], v[174:177], v[142:145], v[2:17]
	v_cvt_pk_bf16_f32 v124, v102, v103
	v_cvt_pk_bf16_f32 v125, v104, v105
	ds_read_b64_tr_b16 v[98:99], v202 offset:33792
	ds_read_b64_tr_b16 v[100:101], v202 offset:34304
	s_waitcnt lgkmcnt(11)
	v_mfma_f32_32x32x16_bf16 v[82:97], v[178:181], v[138:141], v[82:97]
	v_add_f32_e32 v102, v108, v118
	v_add_f32_e32 v102, v109, v102
	v_add_f32_e32 v102, v110, v102
	v_add_f32_e32 v126, v111, v102
	v_cvt_pk_bf16_f32 v118, v106, v107
	v_cvt_pk_bf16_f32 v119, v108, v109
	ds_read_b64_tr_b16 v[102:103], v202 offset:37888
	ds_read_b64_tr_b16 v[104:105], v202 offset:38400
	s_waitcnt lgkmcnt(12)
	v_mfma_f32_32x32x16_bf16 v[50:65], v[170:173], v[138:141], v[50:65]
	v_add_f32_e32 v106, v112, v126
	v_add_f32_e32 v106, v113, v106
	v_add_f32_e32 v106, v66, v106
	v_add_f32_e32 v126, v67, v106
	v_cvt_pk_bf16_f32 v120, v110, v111
	v_cvt_pk_bf16_f32 v121, v112, v113
	ds_read_b64_tr_b16 v[106:107], v202 offset:34816
	ds_read_b64_tr_b16 v[108:109], v202 offset:35328
	s_waitcnt lgkmcnt(13)
	v_mfma_f32_32x32x16_bf16 v[82:97], v[166:169], v[130:133], v[82:97]
	v_add_f32_e32 v110, v68, v126
	v_add_f32_e32 v110, v69, v110
	v_add_f32_e32 v110, v70, v110
	v_add_f32_e32 v110, v71, v110
	v_cvt_pk_bf16_f32 v126, v66, v67
	v_cvt_pk_bf16_f32 v127, v68, v69
	ds_read_b64_tr_b16 v[66:67], v202 offset:38912
	ds_read_b64_tr_b16 v[68:69], v202 offset:39424
	s_waitcnt lgkmcnt(14)
	v_mfma_f32_32x32x16_bf16 v[50:65], v[162:165], v[130:133], v[50:65]
	v_add_f32_e32 v110, v72, v110
	v_add_f32_e32 v110, v73, v110
	v_add_f32_e32 v110, v74, v110
	v_add_f32_e32 v110, v75, v110
	v_cvt_pk_bf16_f32 v128, v70, v71
	v_cvt_pk_bf16_f32 v129, v72, v73
	ds_read_b64_tr_b16 v[70:71], v202 offset:35840
	ds_read_b64_tr_b16 v[72:73], v202 offset:36352
	s_waitcnt lgkmcnt(14)
	v_mfma_f32_32x32x16_bf16 v[82:97], v[158:161], v[114:117], v[82:97]
	v_add_f32_e32 v110, v76, v110
	v_add_f32_e32 v110, v77, v110
	v_add_f32_e32 v110, v78, v110
	v_add_f32_e32 v110, v79, v110
	v_cvt_pk_bf16_f32 v134, v74, v75
	v_cvt_pk_bf16_f32 v135, v76, v77
	ds_read_b64_tr_b16 v[74:75], v202 offset:39936
	ds_read_b64_tr_b16 v[76:77], v202 offset:40448
	v_mfma_f32_32x32x16_bf16 v[50:65], v[154:157], v[114:117], v[50:65]
	v_add_f32_e32 v110, v80, v110
	v_add_f32_e32 v110, v81, v110
	v_add_f32_e32 v110, 0, v110
	v_cvt_pk_bf16_f32 v136, v78, v79
	v_cvt_pk_bf16_f32 v137, v80, v81
	s_mov_b64 s[0:1], 0x38a8000
	v_lshl_add_u64 v[78:79], v[192:193], 0, s[0:1]
	s_mov_b32 m0, s3
	s_nop 0
	global_load_lds_dwordx4 v[78:79], off
	v_max_f32_e32 v78, v83, v83
	v_max_f32_e32 v79, v82, v82
	v_max_f32_e32 v78, v79, v78
	s_nop 1
	v_max3_f32 v79, v84, v85, v51
	v_max3_f32 v78, v78, v50, v52
	v_max3_f32 v78, v78, v53, v86
	v_max3_f32 v79, v79, v88, v89
	v_max3_f32 v78, v78, v87, v54
	v_max3_f32 v79, v79, v56, v57
	v_max3_f32 v78, v78, v55, v90
	v_max3_f32 v79, v79, v92, v93
	v_max3_f32 v78, v78, v91, v58
	v_max3_f32 v79, v79, v60, v61
	v_max3_f32 v78, v78, v59, v94
	v_max3_f32 v79, v79, v96, v97
	v_max3_f32 v78, v78, v95, v62
	v_max3_f32 v79, v79, v64, v65
	v_max3_f32 v78, v78, v63, v79
	v_mov_b32_e32 v79, v78
	s_nop 1
	v_permlane32_swap_b32_e32 v78, v79
	v_max_f32_e32 v79, v79, v79
	v_max_f32_e32 v78, v78, v78
	v_max_f32_e32 v78, v78, v79
	v_cmp_lt_f32_e32 vcc, s51, v78
	s_cmp_lg_u64 vcc, 0
	v_add_f32_e32 v170, v204, v110
	s_cselect_b64 s[0:1], -1, 0
	s_cbranch_vccnz .LBB0_905
